# v6: + log-sigmoid epilogue uses v_log*ln2 under the existing clamp, ple epilogue gate loads hoisted
# speedup vs baseline: 1.0138x; 1.0138x over previous
; DI u32x4 pk8(f32x4 a, f32x4 b) { u32x4 r; r.x = pk2(a[0], a[1]); r.y = pk2(a[2], a[3]); r.z = pk2(b[0], b[1]); r.w = pk2(b[2], b[3]); return r; }
; DI float sigm(float x) { return __builtin_amdgcn_rcpf(1.0f + __expf(-x)); }
;     DI void operator()(const Acc& acc, const pg8::Unit& u, int wr, int wc, int fr, int fq) const {
;     ...
;                     for (int m = 0; m < 4; ++m) { const int row = row0 + ai * 128 + m * 16; f32x4 v0 = acc[ai][bj][m][0], v1 = acc[ai][bj][m][1];
;                         if (seg == 0 || seg == 4) {
; #pragma unroll
;                             for (int j = 0; j < 4; ++j) { v0[j] = v0[j] * sigm(v0[j]); v1[j] = v1[j] * sigm(v1[j]); }
;                         } else if (seg == 1 || seg == 2) {
; #pragma unroll
;                             for (int j = 0; j < 4; ++j) { v0[j] = fmaxf(__logf(l0[j] + (1.0f - l0[j]) * sigm(v0[j])), -30.0f); v1[j] = fmaxf(__logf(l1[j] + (1.0f - l1[j]) * sigm(v1[j])), -30.0f); }
;                         }
;                         *(u32x4*)(dst + (size_t)row * 512 + col) = pk8(v0, v1); } }
.LBB0_458:
	s_cmp_lg_u32 s0, 4
	s_cselect_b64 s[4:5], -1, 0
	s_xor_b64 s[12:13], s[12:13], -1
	s_and_b64 s[12:13], s[12:13], s[4:5]
	v_cndmask_b32_e64 v136, 0, 1, s[14:15]
	s_mov_b64 s[16:17], -1
	s_and_b64 vcc, exec, s[12:13]
	v_cmp_ne_u32_e64 s[40:41], 1, v136
	s_cbranch_vccz .LBB0_462
	v_mov_b64_e32 v[142:143], v[122:123]
	v_mov_b64_e32 v[138:139], v[126:127]
	s_and_b64 vcc, exec, s[40:41]
	v_mov_b64_e32 v[140:141], v[120:121]
	v_mov_b64_e32 v[136:137], v[124:125]
	s_cbranch_vccnz .LBB0_461
	v_mul_f32_e32 v136, 0xbfb8aa3b, v124
	v_exp_f32_e32 v136, v136
	v_mul_f32_e32 v137, 0xbfb8aa3b, v120
	v_exp_f32_e32 v137, v137
	s_waitcnt vmcnt(0)
	v_sub_f32_e32 v138, 1.0, v132
	v_add_f32_e32 v136, 1.0, v136
	v_rcp_f32_e32 v136, v136
	s_mov_b32 s0, 0x800000
	v_add_f32_e32 v137, 1.0, v137
	v_rcp_f32_e32 v137, v137
	v_fma_f32 v136, v136, v138, v132
	v_mul_f32_e32 v139, 0xbfb8aa3b, v125
	v_exp_f32_e32 v139, v139
	v_log_f32_e32 v136, v136
	v_sub_f32_e32 v138, 1.0, v128
	v_fma_f32 v137, v137, v138, v128
	v_add_f32_e32 v139, 1.0, v139
	v_rcp_f32_e32 v139, v139
	v_mul_f32_e32 v141, 0xbfb8aa3b, v126
	v_mul_f32_e32 v136, 0x3f317217, v136
	v_exp_f32_e32 v141, v141
	v_mul_f32_e32 v142, 0xbfb8aa3b, v122
	v_log_f32_e32 v137, v137
	v_add_f32_e32 v141, 1.0, v141
	v_rcp_f32_e32 v141, v141
	v_exp_f32_e32 v142, v142
	v_mul_f32_e32 v137, 0x3f317217, v137
	v_sub_f32_e32 v138, 1.0, v133
	v_fma_f32 v138, v139, v138, v133
	v_add_f32_e32 v142, 1.0, v142
	v_rcp_f32_e32 v142, v142
	v_mul_f32_e32 v139, 0xbfb8aa3b, v121
	v_log_f32_e32 v138, v138
	v_exp_f32_e32 v139, v139
	v_max_f32_e32 v140, 0xc1f00000, v137
	v_mul_f32_e32 v143, 0xbfb8aa3b, v127
	v_add_f32_e32 v139, 1.0, v139
	v_rcp_f32_e32 v139, v139
	v_exp_f32_e32 v143, v143
	v_mul_f32_e32 v155, 0xbfb8aa3b, v123
	v_mul_f32_e32 v137, 0x3f317217, v138
	v_sub_f32_e32 v138, 1.0, v129
	v_fma_f32 v138, v139, v138, v129
	v_add_f32_e32 v143, 1.0, v143
	v_rcp_f32_e32 v143, v143
	v_log_f32_e32 v138, v138
	v_exp_f32_e32 v155, v155
	s_nop 0
	v_add_f32_e32 v155, 1.0, v155
	v_rcp_f32_e32 v155, v155
	v_mul_f32_e32 v138, 0x3f317217, v138
	v_sub_f32_e32 v139, 1.0, v134
	v_fma_f32 v139, v141, v139, v134
	v_max_f32_e32 v136, 0xc1f00000, v136
	v_max_f32_e32 v137, 0xc1f00000, v137
	v_log_f32_e32 v139, v139
	v_max_f32_e32 v141, 0xc1f00000, v138
	s_nop 1
	v_mul_f32_e32 v138, 0x3f317217, v139
	v_sub_f32_e32 v139, 1.0, v130
	v_fma_f32 v139, v142, v139, v130
	s_nop 1
	v_log_f32_e32 v139, v139
	v_max_f32_e32 v138, 0xc1f00000, v138
	s_nop 1
	v_mul_f32_e32 v139, 0x3f317217, v139
	v_sub_f32_e32 v142, 1.0, v135
	v_fma_f32 v142, v143, v142, v135
	s_nop 1
	v_log_f32_e32 v143, v142
	v_max_f32_e32 v142, 0xc1f00000, v139
	s_nop 1
	v_mul_f32_e32 v139, 0x3f317217, v143
	v_sub_f32_e32 v143, 1.0, v131
	v_fma_f32 v143, v155, v143, v131
	s_nop 1
	v_log_f32_e32 v143, v143
	v_max_f32_e32 v139, 0xc1f00000, v139
	s_nop 1
	v_mul_f32_e32 v143, 0x3f317217, v143
	v_max_f32_e32 v143, 0xc1f00000, v143

; DI u32x4 pk8(f32x4 a, f32x4 b) { u32x4 r; r.x = pk2(a[0], a[1]); r.y = pk2(a[2], a[3]); r.z = pk2(b[0], b[1]); r.w = pk2(b[2], b[3]); return r; }
; DI float sigm(float x) { return __builtin_amdgcn_rcpf(1.0f + __expf(-x)); }
;     DI void operator()(const Acc& acc, const pg8::Unit& u, int wr, int wc, int fr, int fq) const {
;     ...
;                     for (int m = 0; m < 4; ++m) { const int row = row0 + ai * 128 + m * 16; f32x4 v0 = acc[ai][bj][m][0], v1 = acc[ai][bj][m][1];
;                         if (seg == 0 || seg == 4) {
; #pragma unroll
;                             for (int j = 0; j < 4; ++j) { v0[j] = v0[j] * sigm(v0[j]); v1[j] = v1[j] * sigm(v1[j]); }
;                         } else if (seg == 1 || seg == 2) {
; #pragma unroll
;                             for (int j = 0; j < 4; ++j) { v0[j] = fmaxf(__logf(l0[j] + (1.0f - l0[j]) * sigm(v0[j])), -30.0f); v1[j] = fmaxf(__logf(l1[j] + (1.0f - l1[j]) * sigm(v1[j])), -30.0f); }
;                         }
;                         *(u32x4*)(dst + (size_t)row * 512 + col) = pk8(v0, v1); } }
.LBB0_464:
	v_ashrrev_i32_e32 v157, 31, v156
	v_lshl_add_u64 v[182:183], v[158:159], 1, s[2:3]
	v_lshlrev_b64 v[160:161], 10, v[156:157]
	v_cvt_pk_bf16_f32 v136, v136, v137
	v_cvt_pk_bf16_f32 v137, v138, v139
	v_cvt_pk_bf16_f32 v138, v140, v141
	v_cvt_pk_bf16_f32 v139, v142, v143
	v_lshl_add_u64 v[140:141], v[182:183], 0, v[160:161]
	global_store_dwordx4 v[140:141], v[136:139], off
	s_andn2_b64 vcc, exec, s[12:13]
	s_nop 0
	v_cndmask_b32_e64 v136, 0, 1, s[12:13]
	v_cmp_ne_u32_e64 s[42:43], 1, v136
	s_mov_b64 s[12:13], -1
	s_cbranch_vccnz .LBB0_468
	v_mov_b64_e32 v[142:143], v[106:107]
	v_mov_b64_e32 v[138:139], v[110:111]
	s_and_b64 vcc, exec, s[40:41]
	v_mov_b64_e32 v[140:141], v[104:105]
	v_mov_b64_e32 v[136:137], v[108:109]
	s_cbranch_vccnz .LBB0_467
	v_mul_f32_e32 v136, 0xbfb8aa3b, v108
	v_exp_f32_e32 v136, v136
	v_mul_f32_e32 v137, 0xbfb8aa3b, v104
	v_exp_f32_e32 v137, v137
	s_waitcnt vmcnt(0)
	v_sub_f32_e32 v138, 1.0, v132
	v_add_f32_e32 v136, 1.0, v136
	v_rcp_f32_e32 v136, v136
	s_mov_b32 s0, 0x800000
	v_add_f32_e32 v137, 1.0, v137
	v_rcp_f32_e32 v137, v137
	v_fma_f32 v136, v136, v138, v132
	v_mul_f32_e32 v139, 0xbfb8aa3b, v109
	v_exp_f32_e32 v139, v139
	v_log_f32_e32 v136, v136
	v_sub_f32_e32 v138, 1.0, v128
	v_fma_f32 v137, v137, v138, v128
	v_add_f32_e32 v139, 1.0, v139
	v_rcp_f32_e32 v139, v139
	v_mul_f32_e32 v141, 0xbfb8aa3b, v110
	v_mul_f32_e32 v136, 0x3f317217, v136
	v_exp_f32_e32 v141, v141
	v_mul_f32_e32 v142, 0xbfb8aa3b, v106
	v_log_f32_e32 v137, v137
	v_add_f32_e32 v141, 1.0, v141
	v_rcp_f32_e32 v141, v141
	v_exp_f32_e32 v142, v142
	v_mul_f32_e32 v137, 0x3f317217, v137
	v_sub_f32_e32 v138, 1.0, v133
	v_fma_f32 v138, v139, v138, v133
	v_add_f32_e32 v142, 1.0, v142
	v_rcp_f32_e32 v142, v142
	v_mul_f32_e32 v139, 0xbfb8aa3b, v105
	v_log_f32_e32 v138, v138
	v_exp_f32_e32 v139, v139
	v_max_f32_e32 v140, 0xc1f00000, v137
	v_mul_f32_e32 v143, 0xbfb8aa3b, v111
	v_add_f32_e32 v139, 1.0, v139
	v_rcp_f32_e32 v139, v139
	v_exp_f32_e32 v143, v143
	v_mul_f32_e32 v155, 0xbfb8aa3b, v107
	v_mul_f32_e32 v137, 0x3f317217, v138
	v_sub_f32_e32 v138, 1.0, v129
	v_fma_f32 v138, v139, v138, v129
	v_add_f32_e32 v143, 1.0, v143
	v_rcp_f32_e32 v143, v143
	v_log_f32_e32 v138, v138
	v_exp_f32_e32 v155, v155
	s_nop 0
	v_add_f32_e32 v155, 1.0, v155
	v_rcp_f32_e32 v155, v155
	v_mul_f32_e32 v138, 0x3f317217, v138
	v_sub_f32_e32 v139, 1.0, v134
	v_fma_f32 v139, v141, v139, v134
	v_max_f32_e32 v136, 0xc1f00000, v136
	v_max_f32_e32 v137, 0xc1f00000, v137
	v_log_f32_e32 v139, v139
	v_max_f32_e32 v141, 0xc1f00000, v138
	s_nop 1
	v_mul_f32_e32 v138, 0x3f317217, v139
	v_sub_f32_e32 v139, 1.0, v130
	v_fma_f32 v139, v142, v139, v130
	s_nop 1
	v_log_f32_e32 v139, v139
	v_max_f32_e32 v138, 0xc1f00000, v138
	s_nop 1
	v_mul_f32_e32 v139, 0x3f317217, v139
	v_sub_f32_e32 v142, 1.0, v135
	v_fma_f32 v142, v143, v142, v135
	s_nop 1
	v_log_f32_e32 v143, v142
	v_max_f32_e32 v142, 0xc1f00000, v139
	s_nop 1
	v_mul_f32_e32 v139, 0x3f317217, v143
	v_sub_f32_e32 v143, 1.0, v131
	v_fma_f32 v143, v155, v143, v131
	s_nop 1
	v_log_f32_e32 v143, v143
	v_max_f32_e32 v139, 0xc1f00000, v139
	s_nop 1
	v_mul_f32_e32 v143, 0x3f317217, v143
	v_max_f32_e32 v143, 0xc1f00000, v143

; DI u32x4 pk8(f32x4 a, f32x4 b) { u32x4 r; r.x = pk2(a[0], a[1]); r.y = pk2(a[2], a[3]); r.z = pk2(b[0], b[1]); r.w = pk2(b[2], b[3]); return r; }
; DI float sigm(float x) { return __builtin_amdgcn_rcpf(1.0f + __expf(-x)); }
;     DI void operator()(const Acc& acc, const pg8::Unit& u, int wr, int wc, int fr, int fq) const {
;     ...
;                     for (int m = 0; m < 4; ++m) { const int row = row0 + ai * 128 + m * 16; f32x4 v0 = acc[ai][bj][m][0], v1 = acc[ai][bj][m][1];
;                         if (seg == 0 || seg == 4) {
; #pragma unroll
;                             for (int j = 0; j < 4; ++j) { v0[j] = v0[j] * sigm(v0[j]); v1[j] = v1[j] * sigm(v1[j]); }
;                         } else if (seg == 1 || seg == 2) {
; #pragma unroll
;                             for (int j = 0; j < 4; ++j) { v0[j] = fmaxf(__logf(l0[j] + (1.0f - l0[j]) * sigm(v0[j])), -30.0f); v1[j] = fmaxf(__logf(l1[j] + (1.0f - l1[j]) * sigm(v1[j])), -30.0f); }
;                         }
;                         *(u32x4*)(dst + (size_t)row * 512 + col) = pk8(v0, v1); } }
.LBB0_470:
	v_cvt_pk_bf16_f32 v136, v136, v137
	v_cvt_pk_bf16_f32 v137, v138, v139
	v_cvt_pk_bf16_f32 v138, v140, v141
	v_lshlrev_b64 v[140:141], 10, v[156:157]
	s_mov_b64 s[4:5], 0x4000
	v_lshl_add_u64 v[162:163], v[140:141], 0, s[4:5]
	v_cvt_pk_bf16_f32 v139, v142, v143
	v_lshl_add_u64 v[140:141], v[182:183], 0, v[162:163]
	s_and_b64 vcc, exec, s[42:43]
	s_mov_b64 s[12:13], -1
	global_store_dwordx4 v[140:141], v[136:139], off
	s_cbranch_vccnz .LBB0_474
	v_mov_b64_e32 v[142:143], v[90:91]
	v_mov_b64_e32 v[138:139], v[94:95]
	s_and_b64 vcc, exec, s[40:41]
	v_mov_b64_e32 v[140:141], v[88:89]
	v_mov_b64_e32 v[136:137], v[92:93]
	s_cbranch_vccnz .LBB0_473
	v_mul_f32_e32 v136, 0xbfb8aa3b, v92
	v_exp_f32_e32 v136, v136
	v_mul_f32_e32 v137, 0xbfb8aa3b, v88
	v_exp_f32_e32 v137, v137
	s_waitcnt vmcnt(0)
	v_sub_f32_e32 v138, 1.0, v132
	v_add_f32_e32 v136, 1.0, v136
	v_rcp_f32_e32 v136, v136
	s_mov_b32 s0, 0x800000
	v_add_f32_e32 v137, 1.0, v137
	v_rcp_f32_e32 v137, v137
	v_fma_f32 v136, v136, v138, v132
	v_mul_f32_e32 v139, 0xbfb8aa3b, v93
	v_exp_f32_e32 v139, v139
	v_log_f32_e32 v136, v136
	v_sub_f32_e32 v138, 1.0, v128
	v_fma_f32 v137, v137, v138, v128
	v_add_f32_e32 v139, 1.0, v139
	v_rcp_f32_e32 v139, v139
	v_mul_f32_e32 v141, 0xbfb8aa3b, v94
	v_mul_f32_e32 v136, 0x3f317217, v136
	v_exp_f32_e32 v141, v141
	v_mul_f32_e32 v142, 0xbfb8aa3b, v90
	v_log_f32_e32 v137, v137
	v_add_f32_e32 v141, 1.0, v141
	v_rcp_f32_e32 v141, v141
	v_exp_f32_e32 v142, v142
	v_mul_f32_e32 v137, 0x3f317217, v137
	v_sub_f32_e32 v138, 1.0, v133
	v_fma_f32 v138, v139, v138, v133
	v_add_f32_e32 v142, 1.0, v142
	v_rcp_f32_e32 v142, v142
	v_mul_f32_e32 v139, 0xbfb8aa3b, v89
	v_log_f32_e32 v138, v138
	v_exp_f32_e32 v139, v139
	v_max_f32_e32 v140, 0xc1f00000, v137
	v_mul_f32_e32 v143, 0xbfb8aa3b, v95
	v_add_f32_e32 v139, 1.0, v139
	v_rcp_f32_e32 v139, v139
	v_exp_f32_e32 v143, v143
	v_mul_f32_e32 v155, 0xbfb8aa3b, v91
	v_mul_f32_e32 v137, 0x3f317217, v138
	v_sub_f32_e32 v138, 1.0, v129
	v_fma_f32 v138, v139, v138, v129
	v_add_f32_e32 v143, 1.0, v143
	v_rcp_f32_e32 v143, v143
	v_log_f32_e32 v138, v138
	v_exp_f32_e32 v155, v155
	s_nop 0
	v_add_f32_e32 v155, 1.0, v155
	v_rcp_f32_e32 v155, v155
	v_mul_f32_e32 v138, 0x3f317217, v138
	v_sub_f32_e32 v139, 1.0, v134
	v_fma_f32 v139, v141, v139, v134
	v_max_f32_e32 v136, 0xc1f00000, v136
	v_max_f32_e32 v137, 0xc1f00000, v137
	v_log_f32_e32 v139, v139
	v_max_f32_e32 v141, 0xc1f00000, v138
	s_nop 1
	v_mul_f32_e32 v138, 0x3f317217, v139
	v_sub_f32_e32 v139, 1.0, v130
	v_fma_f32 v139, v142, v139, v130
	s_nop 1
	v_log_f32_e32 v139, v139
	v_max_f32_e32 v138, 0xc1f00000, v138
	s_nop 1
	v_mul_f32_e32 v139, 0x3f317217, v139
	v_sub_f32_e32 v142, 1.0, v135
	v_fma_f32 v142, v143, v142, v135
	s_nop 1
	v_log_f32_e32 v143, v142
	v_max_f32_e32 v142, 0xc1f00000, v139
	s_nop 1
	v_mul_f32_e32 v139, 0x3f317217, v143
	v_sub_f32_e32 v143, 1.0, v131
	v_fma_f32 v143, v155, v143, v131
	s_nop 1
	v_log_f32_e32 v143, v143
	v_max_f32_e32 v139, 0xc1f00000, v139
	s_nop 1
	v_mul_f32_e32 v143, 0x3f317217, v143
	v_max_f32_e32 v143, 0xc1f00000, v143

; DI u32x4 pk8(f32x4 a, f32x4 b) { u32x4 r; r.x = pk2(a[0], a[1]); r.y = pk2(a[2], a[3]); r.z = pk2(b[0], b[1]); r.w = pk2(b[2], b[3]); return r; }
; DI float sigm(float x) { return __builtin_amdgcn_rcpf(1.0f + __expf(-x)); }
;     DI void operator()(const Acc& acc, const pg8::Unit& u, int wr, int wc, int fr, int fq) const {
;     ...
;                     for (int m = 0; m < 4; ++m) { const int row = row0 + ai * 128 + m * 16; f32x4 v0 = acc[ai][bj][m][0], v1 = acc[ai][bj][m][1];
;                         if (seg == 0 || seg == 4) {
; #pragma unroll
;                             for (int j = 0; j < 4; ++j) { v0[j] = v0[j] * sigm(v0[j]); v1[j] = v1[j] * sigm(v1[j]); }
;                         } else if (seg == 1 || seg == 2) {
; #pragma unroll
;                             for (int j = 0; j < 4; ++j) { v0[j] = fmaxf(__logf(l0[j] + (1.0f - l0[j]) * sigm(v0[j])), -30.0f); v1[j] = fmaxf(__logf(l1[j] + (1.0f - l1[j]) * sigm(v1[j])), -30.0f); }
;                         }
;                         *(u32x4*)(dst + (size_t)row * 512 + col) = pk8(v0, v1); } }
.LBB0_476:
	v_cvt_pk_bf16_f32 v136, v136, v137
	v_cvt_pk_bf16_f32 v137, v138, v139
	v_cvt_pk_bf16_f32 v138, v140, v141
	v_lshlrev_b64 v[140:141], 10, v[156:157]
	s_mov_b64 s[4:5], 0x8000
	v_lshl_add_u64 v[170:171], v[140:141], 0, s[4:5]
	v_cvt_pk_bf16_f32 v139, v142, v143
	v_lshl_add_u64 v[140:141], v[182:183], 0, v[170:171]
	s_and_b64 vcc, exec, s[42:43]
	s_mov_b64 s[12:13], -1
	global_store_dwordx4 v[140:141], v[136:139], off
	s_cbranch_vccnz .LBB0_480
	v_mov_b64_e32 v[142:143], v[74:75]
	v_mov_b64_e32 v[138:139], v[78:79]
	s_and_b64 vcc, exec, s[40:41]
	v_mov_b64_e32 v[140:141], v[72:73]
	v_mov_b64_e32 v[136:137], v[76:77]
	s_cbranch_vccnz .LBB0_479
	v_mul_f32_e32 v136, 0xbfb8aa3b, v76
	v_exp_f32_e32 v136, v136
	v_mul_f32_e32 v137, 0xbfb8aa3b, v72
	v_exp_f32_e32 v137, v137
	s_waitcnt vmcnt(0)
	v_sub_f32_e32 v138, 1.0, v132
	v_add_f32_e32 v136, 1.0, v136
	v_rcp_f32_e32 v136, v136
	s_mov_b32 s0, 0x800000
	v_add_f32_e32 v137, 1.0, v137
	v_rcp_f32_e32 v137, v137
	v_fma_f32 v136, v136, v138, v132
	v_mul_f32_e32 v139, 0xbfb8aa3b, v77
	v_exp_f32_e32 v139, v139
	v_log_f32_e32 v136, v136
	v_sub_f32_e32 v138, 1.0, v128
	v_fma_f32 v137, v137, v138, v128
	v_add_f32_e32 v139, 1.0, v139
	v_rcp_f32_e32 v139, v139
	v_mul_f32_e32 v141, 0xbfb8aa3b, v78
	v_mul_f32_e32 v136, 0x3f317217, v136
	v_exp_f32_e32 v141, v141
	v_mul_f32_e32 v142, 0xbfb8aa3b, v74
	v_log_f32_e32 v137, v137
	v_add_f32_e32 v141, 1.0, v141
	v_rcp_f32_e32 v141, v141
	v_exp_f32_e32 v142, v142
	v_mul_f32_e32 v137, 0x3f317217, v137
	v_sub_f32_e32 v138, 1.0, v133
	v_fma_f32 v138, v139, v138, v133
	v_add_f32_e32 v142, 1.0, v142
	v_rcp_f32_e32 v142, v142
	v_mul_f32_e32 v139, 0xbfb8aa3b, v73
	v_log_f32_e32 v138, v138
	v_exp_f32_e32 v139, v139
	v_max_f32_e32 v140, 0xc1f00000, v137
	v_mul_f32_e32 v143, 0xbfb8aa3b, v79
	v_add_f32_e32 v139, 1.0, v139
	v_rcp_f32_e32 v139, v139
	v_exp_f32_e32 v143, v143
	v_mul_f32_e32 v155, 0xbfb8aa3b, v75
	v_mul_f32_e32 v137, 0x3f317217, v138
	v_sub_f32_e32 v138, 1.0, v129
	v_fma_f32 v138, v139, v138, v129
	v_add_f32_e32 v143, 1.0, v143
	v_rcp_f32_e32 v143, v143
	v_log_f32_e32 v138, v138
	v_exp_f32_e32 v155, v155
	s_nop 0
	v_add_f32_e32 v155, 1.0, v155
	v_rcp_f32_e32 v155, v155
	v_mul_f32_e32 v138, 0x3f317217, v138
	v_sub_f32_e32 v139, 1.0, v134
	v_fma_f32 v139, v141, v139, v134
	v_max_f32_e32 v136, 0xc1f00000, v136
	v_max_f32_e32 v137, 0xc1f00000, v137
	v_log_f32_e32 v139, v139
	v_max_f32_e32 v141, 0xc1f00000, v138
	s_nop 1
	v_mul_f32_e32 v138, 0x3f317217, v139
	v_sub_f32_e32 v139, 1.0, v130
	v_fma_f32 v139, v142, v139, v130
	s_nop 1
	v_log_f32_e32 v139, v139
	v_max_f32_e32 v138, 0xc1f00000, v138
	s_nop 1
	v_mul_f32_e32 v139, 0x3f317217, v139
	v_sub_f32_e32 v142, 1.0, v135
	v_fma_f32 v142, v143, v142, v135
	s_nop 1
	v_log_f32_e32 v143, v142
	v_max_f32_e32 v142, 0xc1f00000, v139
	s_nop 1
	v_mul_f32_e32 v139, 0x3f317217, v143
	v_sub_f32_e32 v143, 1.0, v131
	v_fma_f32 v143, v155, v143, v131
	s_nop 1
	v_log_f32_e32 v143, v143
	v_max_f32_e32 v139, 0xc1f00000, v139
	s_nop 1
	v_mul_f32_e32 v143, 0x3f317217, v143
	v_max_f32_e32 v143, 0xc1f00000, v143

; DI u32x4 pk8(f32x4 a, f32x4 b) { u32x4 r; r.x = pk2(a[0], a[1]); r.y = pk2(a[2], a[3]); r.z = pk2(b[0], b[1]); r.w = pk2(b[2], b[3]); return r; }
; DI float sigm(float x) { return __builtin_amdgcn_rcpf(1.0f + __expf(-x)); }
;     DI void operator()(const Acc& acc, const pg8::Unit& u, int wr, int wc, int fr, int fq) const {
;     ...
;                     for (int m = 0; m < 4; ++m) { const int row = row0 + ai * 128 + m * 16; f32x4 v0 = acc[ai][bj][m][0], v1 = acc[ai][bj][m][1];
;                         if (seg == 0 || seg == 4) {
; #pragma unroll
;                             for (int j = 0; j < 4; ++j) { v0[j] = v0[j] * sigm(v0[j]); v1[j] = v1[j] * sigm(v1[j]); }
;                         } else if (seg == 1 || seg == 2) {
; #pragma unroll
;                             for (int j = 0; j < 4; ++j) { v0[j] = fmaxf(__logf(l0[j] + (1.0f - l0[j]) * sigm(v0[j])), -30.0f); v1[j] = fmaxf(__logf(l1[j] + (1.0f - l1[j]) * sigm(v1[j])), -30.0f); }
;                         }
;                         *(u32x4*)(dst + (size_t)row * 512 + col) = pk8(v0, v1); } }
.LBB0_482:
	v_cvt_pk_bf16_f32 v136, v136, v137
	v_cvt_pk_bf16_f32 v137, v138, v139
	v_cvt_pk_bf16_f32 v138, v140, v141
	v_lshlrev_b64 v[140:141], 10, v[156:157]
	s_mov_b64 s[4:5], 0xc000
	v_lshl_add_u64 v[172:173], v[140:141], 0, s[4:5]
	v_cvt_pk_bf16_f32 v139, v142, v143
	v_lshl_add_u64 v[140:141], v[182:183], 0, v[172:173]
	s_and_b64 vcc, exec, s[42:43]
	s_mov_b64 s[12:13], -1
	global_store_dwordx4 v[140:141], v[136:139], off
	s_cbranch_vccnz .LBB0_486
	v_mov_b64_e32 v[142:143], v[58:59]
	v_mov_b64_e32 v[138:139], v[62:63]
	s_and_b64 vcc, exec, s[40:41]
	v_mov_b64_e32 v[140:141], v[56:57]
	v_mov_b64_e32 v[136:137], v[60:61]
	s_cbranch_vccnz .LBB0_485
	v_mul_f32_e32 v136, 0xbfb8aa3b, v60
	v_exp_f32_e32 v136, v136
	v_mul_f32_e32 v137, 0xbfb8aa3b, v56
	v_exp_f32_e32 v137, v137
	s_waitcnt vmcnt(0)
	v_sub_f32_e32 v138, 1.0, v132
	v_add_f32_e32 v136, 1.0, v136
	v_rcp_f32_e32 v136, v136
	s_mov_b32 s0, 0x800000
	v_add_f32_e32 v137, 1.0, v137
	v_rcp_f32_e32 v137, v137
	v_fma_f32 v136, v136, v138, v132
	v_mul_f32_e32 v139, 0xbfb8aa3b, v61
	v_exp_f32_e32 v139, v139
	v_log_f32_e32 v136, v136
	v_sub_f32_e32 v138, 1.0, v128
	v_fma_f32 v137, v137, v138, v128
	v_add_f32_e32 v139, 1.0, v139
	v_rcp_f32_e32 v139, v139
	v_mul_f32_e32 v141, 0xbfb8aa3b, v62
	v_mul_f32_e32 v136, 0x3f317217, v136
	v_exp_f32_e32 v141, v141
	v_mul_f32_e32 v142, 0xbfb8aa3b, v58
	v_log_f32_e32 v137, v137
	v_add_f32_e32 v141, 1.0, v141
	v_rcp_f32_e32 v141, v141
	v_exp_f32_e32 v142, v142
	v_mul_f32_e32 v137, 0x3f317217, v137
	v_sub_f32_e32 v138, 1.0, v133
	v_fma_f32 v138, v139, v138, v133
	v_add_f32_e32 v142, 1.0, v142
	v_rcp_f32_e32 v142, v142
	v_mul_f32_e32 v139, 0xbfb8aa3b, v57
	v_log_f32_e32 v138, v138
	v_exp_f32_e32 v139, v139
	v_max_f32_e32 v140, 0xc1f00000, v137
	v_mul_f32_e32 v143, 0xbfb8aa3b, v63
	v_add_f32_e32 v139, 1.0, v139
	v_rcp_f32_e32 v139, v139
	v_exp_f32_e32 v143, v143
	v_mul_f32_e32 v155, 0xbfb8aa3b, v59
	v_mul_f32_e32 v137, 0x3f317217, v138
	v_sub_f32_e32 v138, 1.0, v129
	v_fma_f32 v138, v139, v138, v129
	v_add_f32_e32 v143, 1.0, v143
	v_rcp_f32_e32 v143, v143
	v_log_f32_e32 v138, v138
	v_exp_f32_e32 v155, v155
	s_nop 0
	v_add_f32_e32 v155, 1.0, v155
	v_rcp_f32_e32 v155, v155
	v_mul_f32_e32 v138, 0x3f317217, v138
	v_sub_f32_e32 v139, 1.0, v134
	v_fma_f32 v139, v141, v139, v134
	v_max_f32_e32 v136, 0xc1f00000, v136
	v_max_f32_e32 v137, 0xc1f00000, v137
	v_log_f32_e32 v139, v139
	v_max_f32_e32 v141, 0xc1f00000, v138
	s_nop 1
	v_mul_f32_e32 v138, 0x3f317217, v139
	v_sub_f32_e32 v139, 1.0, v130
	v_fma_f32 v139, v142, v139, v130
	s_nop 1
	v_log_f32_e32 v139, v139
	v_max_f32_e32 v138, 0xc1f00000, v138
	s_nop 1
	v_mul_f32_e32 v139, 0x3f317217, v139
	v_sub_f32_e32 v142, 1.0, v135
	v_fma_f32 v142, v143, v142, v135
	s_nop 1
	v_log_f32_e32 v143, v142
	v_max_f32_e32 v142, 0xc1f00000, v139
	s_nop 1
	v_mul_f32_e32 v139, 0x3f317217, v143
	v_sub_f32_e32 v143, 1.0, v131
	v_fma_f32 v143, v155, v143, v131
	s_nop 1
	v_log_f32_e32 v143, v143
	v_max_f32_e32 v139, 0xc1f00000, v139
	s_nop 1
	v_mul_f32_e32 v143, 0x3f317217, v143
	v_max_f32_e32 v143, 0xc1f00000, v143

; DI u32x4 pk8(f32x4 a, f32x4 b) { u32x4 r; r.x = pk2(a[0], a[1]); r.y = pk2(a[2], a[3]); r.z = pk2(b[0], b[1]); r.w = pk2(b[2], b[3]); return r; }
; DI float sigm(float x) { return __builtin_amdgcn_rcpf(1.0f + __expf(-x)); }
;     DI void operator()(const Acc& acc, const pg8::Unit& u, int wr, int wc, int fr, int fq) const {
;     ...
;                     for (int m = 0; m < 4; ++m) { const int row = row0 + ai * 128 + m * 16; f32x4 v0 = acc[ai][bj][m][0], v1 = acc[ai][bj][m][1];
;                         if (seg == 0 || seg == 4) {
; #pragma unroll
;                             for (int j = 0; j < 4; ++j) { v0[j] = v0[j] * sigm(v0[j]); v1[j] = v1[j] * sigm(v1[j]); }
;                         } else if (seg == 1 || seg == 2) {
; #pragma unroll
;                             for (int j = 0; j < 4; ++j) { v0[j] = fmaxf(__logf(l0[j] + (1.0f - l0[j]) * sigm(v0[j])), -30.0f); v1[j] = fmaxf(__logf(l1[j] + (1.0f - l1[j]) * sigm(v1[j])), -30.0f); }
;                         }
;                         *(u32x4*)(dst + (size_t)row * 512 + col) = pk8(v0, v1); } }
.LBB0_488:
	v_cvt_pk_bf16_f32 v136, v136, v137
	v_cvt_pk_bf16_f32 v137, v138, v139
	v_cvt_pk_bf16_f32 v138, v140, v141
	v_lshlrev_b64 v[140:141], 10, v[156:157]
	s_mov_b64 s[4:5], 0x20000
	v_lshl_add_u64 v[174:175], v[140:141], 0, s[4:5]
	v_cvt_pk_bf16_f32 v139, v142, v143
	v_lshl_add_u64 v[140:141], v[182:183], 0, v[174:175]
	s_and_b64 vcc, exec, s[42:43]
	s_mov_b64 s[12:13], -1
	global_store_dwordx4 v[140:141], v[136:139], off
	s_cbranch_vccnz .LBB0_492
	v_mov_b64_e32 v[142:143], v[42:43]
	v_mov_b64_e32 v[138:139], v[46:47]
	s_and_b64 vcc, exec, s[40:41]
	v_mov_b64_e32 v[140:141], v[40:41]
	v_mov_b64_e32 v[136:137], v[44:45]
	s_cbranch_vccnz .LBB0_491
	v_mul_f32_e32 v136, 0xbfb8aa3b, v44
	v_exp_f32_e32 v136, v136
	v_mul_f32_e32 v137, 0xbfb8aa3b, v40
	v_exp_f32_e32 v137, v137
	s_waitcnt vmcnt(0)
	v_sub_f32_e32 v138, 1.0, v132
	v_add_f32_e32 v136, 1.0, v136
	v_rcp_f32_e32 v136, v136
	s_mov_b32 s0, 0x800000
	v_add_f32_e32 v137, 1.0, v137
	v_rcp_f32_e32 v137, v137
	v_fma_f32 v136, v136, v138, v132
	v_mul_f32_e32 v139, 0xbfb8aa3b, v45
	v_exp_f32_e32 v139, v139
	v_log_f32_e32 v136, v136
	v_sub_f32_e32 v138, 1.0, v128
	v_fma_f32 v137, v137, v138, v128
	v_add_f32_e32 v139, 1.0, v139
	v_rcp_f32_e32 v139, v139
	v_mul_f32_e32 v141, 0xbfb8aa3b, v46
	v_mul_f32_e32 v136, 0x3f317217, v136
	v_exp_f32_e32 v141, v141
	v_mul_f32_e32 v142, 0xbfb8aa3b, v42
	v_log_f32_e32 v137, v137
	v_add_f32_e32 v141, 1.0, v141
	v_rcp_f32_e32 v141, v141
	v_exp_f32_e32 v142, v142
	v_mul_f32_e32 v137, 0x3f317217, v137
	v_sub_f32_e32 v138, 1.0, v133
	v_fma_f32 v138, v139, v138, v133
	v_add_f32_e32 v142, 1.0, v142
	v_rcp_f32_e32 v142, v142
	v_mul_f32_e32 v139, 0xbfb8aa3b, v41
	v_log_f32_e32 v138, v138
	v_exp_f32_e32 v139, v139
	v_max_f32_e32 v140, 0xc1f00000, v137
	v_mul_f32_e32 v143, 0xbfb8aa3b, v47
	v_add_f32_e32 v139, 1.0, v139
	v_rcp_f32_e32 v139, v139
	v_exp_f32_e32 v143, v143
	v_mul_f32_e32 v155, 0xbfb8aa3b, v43
	v_mul_f32_e32 v137, 0x3f317217, v138
	v_sub_f32_e32 v138, 1.0, v129
	v_fma_f32 v138, v139, v138, v129
	v_add_f32_e32 v143, 1.0, v143
	v_rcp_f32_e32 v143, v143
	v_log_f32_e32 v138, v138
	v_exp_f32_e32 v155, v155
	s_nop 0
	v_add_f32_e32 v155, 1.0, v155
	v_rcp_f32_e32 v155, v155
	v_mul_f32_e32 v138, 0x3f317217, v138
	v_sub_f32_e32 v139, 1.0, v134
	v_fma_f32 v139, v141, v139, v134
	v_max_f32_e32 v136, 0xc1f00000, v136
	v_max_f32_e32 v137, 0xc1f00000, v137
	v_log_f32_e32 v139, v139
	v_max_f32_e32 v141, 0xc1f00000, v138
	s_nop 1
	v_mul_f32_e32 v138, 0x3f317217, v139
	v_sub_f32_e32 v139, 1.0, v130
	v_fma_f32 v139, v142, v139, v130
	s_nop 1
	v_log_f32_e32 v139, v139
	v_max_f32_e32 v138, 0xc1f00000, v138
	s_nop 1
	v_mul_f32_e32 v139, 0x3f317217, v139
	v_sub_f32_e32 v142, 1.0, v135
	v_fma_f32 v142, v143, v142, v135
	s_nop 1
	v_log_f32_e32 v143, v142
	v_max_f32_e32 v142, 0xc1f00000, v139
	s_nop 1
	v_mul_f32_e32 v139, 0x3f317217, v143
	v_sub_f32_e32 v143, 1.0, v131
	v_fma_f32 v143, v155, v143, v131
	s_nop 1
	v_log_f32_e32 v143, v143
	v_max_f32_e32 v139, 0xc1f00000, v139
	s_nop 1
	v_mul_f32_e32 v143, 0x3f317217, v143
	v_max_f32_e32 v143, 0xc1f00000, v143

; DI u32x4 pk8(f32x4 a, f32x4 b) { u32x4 r; r.x = pk2(a[0], a[1]); r.y = pk2(a[2], a[3]); r.z = pk2(b[0], b[1]); r.w = pk2(b[2], b[3]); return r; }
; DI float sigm(float x) { return __builtin_amdgcn_rcpf(1.0f + __expf(-x)); }
;     DI void operator()(const Acc& acc, const pg8::Unit& u, int wr, int wc, int fr, int fq) const {
;     ...
;                     for (int m = 0; m < 4; ++m) { const int row = row0 + ai * 128 + m * 16; f32x4 v0 = acc[ai][bj][m][0], v1 = acc[ai][bj][m][1];
;                         if (seg == 0 || seg == 4) {
; #pragma unroll
;                             for (int j = 0; j < 4; ++j) { v0[j] = v0[j] * sigm(v0[j]); v1[j] = v1[j] * sigm(v1[j]); }
;                         } else if (seg == 1 || seg == 2) {
; #pragma unroll
;                             for (int j = 0; j < 4; ++j) { v0[j] = fmaxf(__logf(l0[j] + (1.0f - l0[j]) * sigm(v0[j])), -30.0f); v1[j] = fmaxf(__logf(l1[j] + (1.0f - l1[j]) * sigm(v1[j])), -30.0f); }
;                         }
;                         *(u32x4*)(dst + (size_t)row * 512 + col) = pk8(v0, v1); } }
.LBB0_494:
	v_cvt_pk_bf16_f32 v136, v136, v137
	v_cvt_pk_bf16_f32 v137, v138, v139
	v_cvt_pk_bf16_f32 v138, v140, v141
	v_lshlrev_b64 v[140:141], 10, v[156:157]
	s_mov_b64 s[4:5], 0x24000
	v_lshl_add_u64 v[176:177], v[140:141], 0, s[4:5]
	v_cvt_pk_bf16_f32 v139, v142, v143
	v_lshl_add_u64 v[140:141], v[182:183], 0, v[176:177]
	s_and_b64 vcc, exec, s[42:43]
	s_mov_b64 s[12:13], -1
	global_store_dwordx4 v[140:141], v[136:139], off
	s_cbranch_vccnz .LBB0_498
	v_mov_b64_e32 v[142:143], v[26:27]
	v_mov_b64_e32 v[138:139], v[30:31]
	s_and_b64 vcc, exec, s[40:41]
	v_mov_b64_e32 v[140:141], v[24:25]
	v_mov_b64_e32 v[136:137], v[28:29]
	s_cbranch_vccnz .LBB0_497
	v_mul_f32_e32 v136, 0xbfb8aa3b, v28
	v_exp_f32_e32 v136, v136
	v_mul_f32_e32 v137, 0xbfb8aa3b, v24
	v_exp_f32_e32 v137, v137
	s_waitcnt vmcnt(0)
	v_sub_f32_e32 v138, 1.0, v132
	v_add_f32_e32 v136, 1.0, v136
	v_rcp_f32_e32 v136, v136
	s_mov_b32 s0, 0x800000
	v_add_f32_e32 v137, 1.0, v137
	v_rcp_f32_e32 v137, v137
	v_fma_f32 v136, v136, v138, v132
	v_mul_f32_e32 v139, 0xbfb8aa3b, v29
	v_exp_f32_e32 v139, v139
	v_log_f32_e32 v136, v136
	v_sub_f32_e32 v138, 1.0, v128
	v_fma_f32 v137, v137, v138, v128
	v_add_f32_e32 v139, 1.0, v139
	v_rcp_f32_e32 v139, v139
	v_mul_f32_e32 v141, 0xbfb8aa3b, v30
	v_mul_f32_e32 v136, 0x3f317217, v136
	v_exp_f32_e32 v141, v141
	v_mul_f32_e32 v142, 0xbfb8aa3b, v26
	v_log_f32_e32 v137, v137
	v_add_f32_e32 v141, 1.0, v141
	v_rcp_f32_e32 v141, v141
	v_exp_f32_e32 v142, v142
	v_mul_f32_e32 v137, 0x3f317217, v137
	v_sub_f32_e32 v138, 1.0, v133
	v_fma_f32 v138, v139, v138, v133
	v_add_f32_e32 v142, 1.0, v142
	v_rcp_f32_e32 v142, v142
	v_mul_f32_e32 v139, 0xbfb8aa3b, v25
	v_log_f32_e32 v138, v138
	v_exp_f32_e32 v139, v139
	v_max_f32_e32 v140, 0xc1f00000, v137
	v_mul_f32_e32 v143, 0xbfb8aa3b, v31
	v_add_f32_e32 v139, 1.0, v139
	v_rcp_f32_e32 v139, v139
	v_exp_f32_e32 v143, v143
	v_mul_f32_e32 v155, 0xbfb8aa3b, v27
	v_mul_f32_e32 v137, 0x3f317217, v138
	v_sub_f32_e32 v138, 1.0, v129
	v_fma_f32 v138, v139, v138, v129
	v_add_f32_e32 v143, 1.0, v143
	v_rcp_f32_e32 v143, v143
	v_log_f32_e32 v138, v138
	v_exp_f32_e32 v155, v155
	s_nop 0
	v_add_f32_e32 v155, 1.0, v155
	v_rcp_f32_e32 v155, v155
	v_mul_f32_e32 v138, 0x3f317217, v138
	v_sub_f32_e32 v139, 1.0, v134
	v_fma_f32 v139, v141, v139, v134
	v_max_f32_e32 v136, 0xc1f00000, v136
	v_max_f32_e32 v137, 0xc1f00000, v137
	v_log_f32_e32 v139, v139
	v_max_f32_e32 v141, 0xc1f00000, v138
	s_nop 1
	v_mul_f32_e32 v138, 0x3f317217, v139
	v_sub_f32_e32 v139, 1.0, v130
	v_fma_f32 v139, v142, v139, v130
	s_nop 1
	v_log_f32_e32 v139, v139
	v_max_f32_e32 v138, 0xc1f00000, v138
	s_nop 1
	v_mul_f32_e32 v139, 0x3f317217, v139
	v_sub_f32_e32 v142, 1.0, v135
	v_fma_f32 v142, v143, v142, v135
	s_nop 1
	v_log_f32_e32 v143, v142
	v_max_f32_e32 v142, 0xc1f00000, v139
	s_nop 1
	v_mul_f32_e32 v139, 0x3f317217, v143
	v_sub_f32_e32 v143, 1.0, v131
	v_fma_f32 v143, v155, v143, v131
	s_nop 1
	v_log_f32_e32 v143, v143
	v_max_f32_e32 v139, 0xc1f00000, v139
	s_nop 1
	v_mul_f32_e32 v143, 0x3f317217, v143
	v_max_f32_e32 v143, 0xc1f00000, v143

; DI u32x4 pk8(f32x4 a, f32x4 b) { u32x4 r; r.x = pk2(a[0], a[1]); r.y = pk2(a[2], a[3]); r.z = pk2(b[0], b[1]); r.w = pk2(b[2], b[3]); return r; }
; DI float sigm(float x) { return __builtin_amdgcn_rcpf(1.0f + __expf(-x)); }
;     DI void operator()(const Acc& acc, const pg8::Unit& u, int wr, int wc, int fr, int fq) const {
;     ...
;                     for (int m = 0; m < 4; ++m) { const int row = row0 + ai * 128 + m * 16; f32x4 v0 = acc[ai][bj][m][0], v1 = acc[ai][bj][m][1];
;                         if (seg == 0 || seg == 4) {
; #pragma unroll
;                             for (int j = 0; j < 4; ++j) { v0[j] = v0[j] * sigm(v0[j]); v1[j] = v1[j] * sigm(v1[j]); }
;                         } else if (seg == 1 || seg == 2) {
; #pragma unroll
;                             for (int j = 0; j < 4; ++j) { v0[j] = fmaxf(__logf(l0[j] + (1.0f - l0[j]) * sigm(v0[j])), -30.0f); v1[j] = fmaxf(__logf(l1[j] + (1.0f - l1[j]) * sigm(v1[j])), -30.0f); }
;                         }
;                         *(u32x4*)(dst + (size_t)row * 512 + col) = pk8(v0, v1); } }
.LBB0_500:
	v_cvt_pk_bf16_f32 v136, v136, v137
	v_cvt_pk_bf16_f32 v137, v138, v139
	v_cvt_pk_bf16_f32 v138, v140, v141
	v_lshlrev_b64 v[140:141], 10, v[156:157]
	s_mov_b64 s[4:5], 0x28000
	v_lshl_add_u64 v[178:179], v[140:141], 0, s[4:5]
	v_cvt_pk_bf16_f32 v139, v142, v143
	v_lshl_add_u64 v[140:141], v[182:183], 0, v[178:179]
	s_and_b64 vcc, exec, s[42:43]
	s_mov_b64 s[12:13], -1
	global_store_dwordx4 v[140:141], v[136:139], off
	s_cbranch_vccnz .LBB0_504
	v_mov_b64_e32 v[142:143], v[10:11]
	v_mov_b64_e32 v[138:139], v[14:15]
	s_and_b64 vcc, exec, s[40:41]
	v_mov_b64_e32 v[140:141], v[8:9]
	v_mov_b64_e32 v[136:137], v[12:13]
	s_cbranch_vccnz .LBB0_503
	v_mul_f32_e32 v137, 0xbfb8aa3b, v12
	v_exp_f32_e32 v137, v137
	s_waitcnt vmcnt(0)
	v_sub_f32_e32 v136, 1.0, v132
	s_mov_b32 s0, 0x800000
	v_add_f32_e32 v137, 1.0, v137
	v_rcp_f32_e32 v137, v137
	s_nop 0
	v_fmac_f32_e32 v132, v137, v136
	v_mul_f32_e32 v137, 0xbfb8aa3b, v8
	v_exp_f32_e32 v137, v137
	v_log_f32_e32 v132, v132
	v_add_f32_e32 v137, 1.0, v137
	v_rcp_f32_e32 v137, v137
	s_nop 1
	v_mul_f32_e32 v132, 0x3f317217, v132
	v_max_f32_e32 v136, 0xc1f00000, v132
	v_sub_f32_e32 v132, 1.0, v128
	v_fmac_f32_e32 v128, v137, v132
	s_nop 1
	v_log_f32_e32 v128, v128
	s_nop 0
	s_nop 1
	v_mul_f32_e32 v128, 0x3f317217, v128
	v_mul_f32_e32 v132, 0xbfb8aa3b, v13
	v_exp_f32_e32 v132, v132
	v_max_f32_e32 v140, 0xc1f00000, v128
	v_sub_f32_e32 v128, 1.0, v133
	v_add_f32_e32 v132, 1.0, v132
	v_rcp_f32_e32 v132, v132
	s_nop 0
	v_fmac_f32_e32 v133, v132, v128
	s_nop 1
	v_log_f32_e32 v128, v133
	s_nop 0
	s_nop 1
	v_mul_f32_e32 v128, 0x3f317217, v128
	v_mul_f32_e32 v132, 0xbfb8aa3b, v9
	v_exp_f32_e32 v132, v132
	v_max_f32_e32 v137, 0xc1f00000, v128
	v_sub_f32_e32 v128, 1.0, v129
	v_add_f32_e32 v132, 1.0, v132
	v_rcp_f32_e32 v132, v132
	s_nop 0
	v_fmac_f32_e32 v129, v132, v128
	s_nop 1
	v_log_f32_e32 v128, v129
	s_nop 0
	s_nop 1
	v_mul_f32_e32 v128, 0x3f317217, v128
	v_mul_f32_e32 v129, 0xbfb8aa3b, v14
	v_exp_f32_e32 v129, v129
	v_max_f32_e32 v141, 0xc1f00000, v128
	v_sub_f32_e32 v128, 1.0, v134
	v_add_f32_e32 v129, 1.0, v129
	v_rcp_f32_e32 v129, v129
	s_nop 0
	v_fmac_f32_e32 v134, v129, v128
	s_nop 1
	v_log_f32_e32 v128, v134
	s_nop 0
	s_nop 1
	v_mul_f32_e32 v128, 0x3f317217, v128
	v_mul_f32_e32 v129, 0xbfb8aa3b, v10
	v_exp_f32_e32 v129, v129
	v_max_f32_e32 v138, 0xc1f00000, v128
	v_sub_f32_e32 v128, 1.0, v130
	v_add_f32_e32 v129, 1.0, v129
	v_rcp_f32_e32 v129, v129
	s_nop 0
	v_fmac_f32_e32 v130, v129, v128
	s_nop 1
	v_log_f32_e32 v128, v130
	s_nop 0
	s_nop 1
	v_mul_f32_e32 v128, 0x3f317217, v128
	v_mul_f32_e32 v129, 0xbfb8aa3b, v15
	v_exp_f32_e32 v129, v129
	v_max_f32_e32 v142, 0xc1f00000, v128
	v_sub_f32_e32 v128, 1.0, v135
	v_add_f32_e32 v129, 1.0, v129
	v_rcp_f32_e32 v129, v129
	s_nop 0
	v_fmac_f32_e32 v135, v129, v128
	s_nop 1
	v_log_f32_e32 v128, v135
	s_nop 0
	s_nop 1
	v_mul_f32_e32 v128, 0x3f317217, v128
	v_mul_f32_e32 v129, 0xbfb8aa3b, v11
	v_exp_f32_e32 v129, v129
	v_max_f32_e32 v139, 0xc1f00000, v128
	v_sub_f32_e32 v128, 1.0, v131
	v_add_f32_e32 v129, 1.0, v129
	v_rcp_f32_e32 v129, v129
	s_nop 0
	v_fmac_f32_e32 v131, v129, v128
	s_nop 1
	v_log_f32_e32 v128, v131
	s_nop 0
	s_nop 1
	v_mul_f32_e32 v128, 0x3f317217, v128
	v_max_f32_e32 v143, 0xc1f00000, v128

; DI u32x4 pk8(f32x4 a, f32x4 b) { u32x4 r; r.x = pk2(a[0], a[1]); r.y = pk2(a[2], a[3]); r.z = pk2(b[0], b[1]); r.w = pk2(b[2], b[3]); return r; }
; DI float sigm(float x) { return __builtin_amdgcn_rcpf(1.0f + __expf(-x)); }
;     DI void operator()(const Acc& acc, const pg8::Unit& u, int wr, int wc, int fr, int fq) const {
;     ...
;                     for (int m = 0; m < 4; ++m) { const int row = row0 + ai * 128 + m * 16; f32x4 v0 = acc[ai][bj][m][0], v1 = acc[ai][bj][m][1];
;                         if (seg == 0 || seg == 4) {
; #pragma unroll
;                             for (int j = 0; j < 4; ++j) { v0[j] = v0[j] * sigm(v0[j]); v1[j] = v1[j] * sigm(v1[j]); }
;                         } else if (seg == 1 || seg == 2) {
; #pragma unroll
;                             for (int j = 0; j < 4; ++j) { v0[j] = fmaxf(__logf(l0[j] + (1.0f - l0[j]) * sigm(v0[j])), -30.0f); v1[j] = fmaxf(__logf(l1[j] + (1.0f - l1[j]) * sigm(v1[j])), -30.0f); }
;                         }
;                         *(u32x4*)(dst + (size_t)row * 512 + col) = pk8(v0, v1); } }
.LBB0_510:
	s_and_b64 vcc, exec, s[42:43]
	s_mov_b64 s[10:11], -1
	s_cbranch_vccnz .LBB0_514
	v_mov_b64_e32 v[142:143], v[114:115]
	v_mov_b64_e32 v[138:139], v[118:119]
	s_and_b64 vcc, exec, s[40:41]
	v_mov_b64_e32 v[140:141], v[112:113]
	v_mov_b64_e32 v[136:137], v[116:117]
	s_cbranch_vccnz .LBB0_513
	v_mul_f32_e32 v136, 0xbfb8aa3b, v116
	v_exp_f32_e32 v136, v136
	v_mul_f32_e32 v137, 0xbfb8aa3b, v112
	v_exp_f32_e32 v137, v137
	s_waitcnt vmcnt(1)
	v_sub_f32_e32 v138, 1.0, v132
	v_add_f32_e32 v136, 1.0, v136
	v_rcp_f32_e32 v136, v136
	s_mov_b32 s0, 0x800000
	v_add_f32_e32 v137, 1.0, v137
	v_rcp_f32_e32 v137, v137
	v_fma_f32 v136, v136, v138, v132
	v_mul_f32_e32 v139, 0xbfb8aa3b, v117
	v_exp_f32_e32 v139, v139
	v_log_f32_e32 v136, v136
	s_waitcnt vmcnt(0)
	v_sub_f32_e32 v138, 1.0, v128
	v_fma_f32 v137, v137, v138, v128
	v_add_f32_e32 v139, 1.0, v139
	v_rcp_f32_e32 v139, v139
	v_mul_f32_e32 v141, 0xbfb8aa3b, v118
	v_mul_f32_e32 v136, 0x3f317217, v136
	v_exp_f32_e32 v141, v141
	v_mul_f32_e32 v142, 0xbfb8aa3b, v114
	v_log_f32_e32 v137, v137
	v_add_f32_e32 v141, 1.0, v141
	v_rcp_f32_e32 v141, v141
	v_exp_f32_e32 v142, v142
	v_mul_f32_e32 v137, 0x3f317217, v137
	v_sub_f32_e32 v138, 1.0, v133
	v_fma_f32 v138, v139, v138, v133
	v_add_f32_e32 v142, 1.0, v142
	v_rcp_f32_e32 v142, v142
	v_mul_f32_e32 v139, 0xbfb8aa3b, v113
	v_log_f32_e32 v138, v138
	v_exp_f32_e32 v139, v139
	v_max_f32_e32 v140, 0xc1f00000, v137
	v_mul_f32_e32 v143, 0xbfb8aa3b, v119
	v_add_f32_e32 v139, 1.0, v139
	v_rcp_f32_e32 v139, v139
	v_exp_f32_e32 v143, v143
	v_mul_f32_e32 v155, 0xbfb8aa3b, v115
	v_mul_f32_e32 v137, 0x3f317217, v138
	v_sub_f32_e32 v138, 1.0, v129
	v_fma_f32 v138, v139, v138, v129
	v_add_f32_e32 v143, 1.0, v143
	v_rcp_f32_e32 v143, v143
	v_log_f32_e32 v138, v138
	v_exp_f32_e32 v155, v155
	s_nop 0
	v_add_f32_e32 v155, 1.0, v155
	v_rcp_f32_e32 v155, v155
	v_mul_f32_e32 v138, 0x3f317217, v138
	v_sub_f32_e32 v139, 1.0, v134
	v_fma_f32 v139, v141, v139, v134
	v_max_f32_e32 v136, 0xc1f00000, v136
	v_max_f32_e32 v137, 0xc1f00000, v137
	v_log_f32_e32 v139, v139
	v_max_f32_e32 v141, 0xc1f00000, v138
	s_nop 1
	v_mul_f32_e32 v138, 0x3f317217, v139
	v_sub_f32_e32 v139, 1.0, v130
	v_fma_f32 v139, v142, v139, v130
	s_nop 1
	v_log_f32_e32 v139, v139
	v_max_f32_e32 v138, 0xc1f00000, v138
	s_nop 1
	v_mul_f32_e32 v139, 0x3f317217, v139
	v_sub_f32_e32 v142, 1.0, v135
	v_fma_f32 v142, v143, v142, v135
	s_nop 1
	v_log_f32_e32 v143, v142
	v_max_f32_e32 v142, 0xc1f00000, v139
	s_nop 1
	v_mul_f32_e32 v139, 0x3f317217, v143
	v_sub_f32_e32 v143, 1.0, v131
	v_fma_f32 v143, v155, v143, v131
	s_nop 1
	v_log_f32_e32 v143, v143
	v_max_f32_e32 v139, 0xc1f00000, v139
	s_nop 1
	v_mul_f32_e32 v143, 0x3f317217, v143
	v_max_f32_e32 v143, 0xc1f00000, v143

; DI u32x4 pk8(f32x4 a, f32x4 b) { u32x4 r; r.x = pk2(a[0], a[1]); r.y = pk2(a[2], a[3]); r.z = pk2(b[0], b[1]); r.w = pk2(b[2], b[3]); return r; }
; DI float sigm(float x) { return __builtin_amdgcn_rcpf(1.0f + __expf(-x)); }
;     DI void operator()(const Acc& acc, const pg8::Unit& u, int wr, int wc, int fr, int fq) const {
;     ...
;                     for (int m = 0; m < 4; ++m) { const int row = row0 + ai * 128 + m * 16; f32x4 v0 = acc[ai][bj][m][0], v1 = acc[ai][bj][m][1];
;                         if (seg == 0 || seg == 4) {
; #pragma unroll
;                             for (int j = 0; j < 4; ++j) { v0[j] = v0[j] * sigm(v0[j]); v1[j] = v1[j] * sigm(v1[j]); }
;                         } else if (seg == 1 || seg == 2) {
; #pragma unroll
;                             for (int j = 0; j < 4; ++j) { v0[j] = fmaxf(__logf(l0[j] + (1.0f - l0[j]) * sigm(v0[j])), -30.0f); v1[j] = fmaxf(__logf(l1[j] + (1.0f - l1[j]) * sigm(v1[j])), -30.0f); }
;                         }
;                         *(u32x4*)(dst + (size_t)row * 512 + col) = pk8(v0, v1); } }
.LBB0_516:
	v_lshl_add_u64 v[158:159], v[182:183], 1, s[2:3]
	v_cvt_pk_bf16_f32 v136, v136, v137
	v_cvt_pk_bf16_f32 v137, v138, v139
	v_cvt_pk_bf16_f32 v138, v140, v141
	v_cvt_pk_bf16_f32 v139, v142, v143
	v_lshl_add_u64 v[140:141], v[158:159], 0, v[160:161]
	s_and_b64 vcc, exec, s[42:43]
	s_mov_b64 s[2:3], -1
	global_store_dwordx4 v[140:141], v[136:139], off
	s_cbranch_vccnz .LBB0_520
	v_mov_b64_e32 v[142:143], v[98:99]
	v_mov_b64_e32 v[138:139], v[102:103]
	s_and_b64 vcc, exec, s[40:41]
	v_mov_b64_e32 v[140:141], v[96:97]
	v_mov_b64_e32 v[136:137], v[100:101]
	s_cbranch_vccnz .LBB0_519
	v_mul_f32_e32 v136, 0xbfb8aa3b, v100
	v_exp_f32_e32 v136, v136
	v_mul_f32_e32 v137, 0xbfb8aa3b, v96
	v_exp_f32_e32 v137, v137
	s_waitcnt vmcnt(2)
	v_sub_f32_e32 v138, 1.0, v132
	v_add_f32_e32 v136, 1.0, v136
	v_rcp_f32_e32 v136, v136
	s_mov_b32 s0, 0x800000
	v_add_f32_e32 v137, 1.0, v137
	v_rcp_f32_e32 v137, v137
	v_fma_f32 v136, v136, v138, v132
	v_mul_f32_e32 v139, 0xbfb8aa3b, v101
	v_exp_f32_e32 v139, v139
	v_log_f32_e32 v136, v136
	s_waitcnt vmcnt(1)
	v_sub_f32_e32 v138, 1.0, v128
	v_fma_f32 v137, v137, v138, v128
	v_add_f32_e32 v139, 1.0, v139
	v_rcp_f32_e32 v139, v139
	v_mul_f32_e32 v141, 0xbfb8aa3b, v102
	v_mul_f32_e32 v136, 0x3f317217, v136
	v_exp_f32_e32 v141, v141
	v_mul_f32_e32 v142, 0xbfb8aa3b, v98
	v_log_f32_e32 v137, v137
	v_add_f32_e32 v141, 1.0, v141
	v_rcp_f32_e32 v141, v141
	v_exp_f32_e32 v142, v142
	v_mul_f32_e32 v137, 0x3f317217, v137
	v_sub_f32_e32 v138, 1.0, v133
	v_fma_f32 v138, v139, v138, v133
	v_add_f32_e32 v142, 1.0, v142
	v_rcp_f32_e32 v142, v142
	v_mul_f32_e32 v139, 0xbfb8aa3b, v97
	v_log_f32_e32 v138, v138
	v_exp_f32_e32 v139, v139
	v_max_f32_e32 v140, 0xc1f00000, v137
	v_mul_f32_e32 v143, 0xbfb8aa3b, v103
	v_add_f32_e32 v139, 1.0, v139
	v_rcp_f32_e32 v139, v139
	v_exp_f32_e32 v143, v143
	v_mul_f32_e32 v155, 0xbfb8aa3b, v99
	v_mul_f32_e32 v137, 0x3f317217, v138
	v_sub_f32_e32 v138, 1.0, v129
	v_fma_f32 v138, v139, v138, v129
	v_add_f32_e32 v143, 1.0, v143
	v_rcp_f32_e32 v143, v143
	v_log_f32_e32 v138, v138
	v_exp_f32_e32 v155, v155
	s_nop 0
	v_add_f32_e32 v155, 1.0, v155
	v_rcp_f32_e32 v155, v155
	v_mul_f32_e32 v138, 0x3f317217, v138
	v_sub_f32_e32 v139, 1.0, v134
	v_fma_f32 v139, v141, v139, v134
	v_max_f32_e32 v136, 0xc1f00000, v136
	v_max_f32_e32 v137, 0xc1f00000, v137
	v_log_f32_e32 v139, v139
	v_max_f32_e32 v141, 0xc1f00000, v138
	s_nop 1
	v_mul_f32_e32 v138, 0x3f317217, v139
	v_sub_f32_e32 v139, 1.0, v130
	v_fma_f32 v139, v142, v139, v130
	s_nop 1
	v_log_f32_e32 v139, v139
	v_max_f32_e32 v138, 0xc1f00000, v138
	s_nop 1
	v_mul_f32_e32 v139, 0x3f317217, v139
	v_sub_f32_e32 v142, 1.0, v135
	v_fma_f32 v142, v143, v142, v135
	s_nop 1
	v_log_f32_e32 v143, v142
	v_max_f32_e32 v142, 0xc1f00000, v139
	s_nop 1
	v_mul_f32_e32 v139, 0x3f317217, v143
	v_sub_f32_e32 v143, 1.0, v131
	v_fma_f32 v143, v155, v143, v131
	s_nop 1
	v_log_f32_e32 v143, v143
	v_max_f32_e32 v139, 0xc1f00000, v139
	s_nop 1
	v_mul_f32_e32 v143, 0x3f317217, v143
	v_max_f32_e32 v143, 0xc1f00000, v143

; DI u32x4 pk8(f32x4 a, f32x4 b) { u32x4 r; r.x = pk2(a[0], a[1]); r.y = pk2(a[2], a[3]); r.z = pk2(b[0], b[1]); r.w = pk2(b[2], b[3]); return r; }
; DI float sigm(float x) { return __builtin_amdgcn_rcpf(1.0f + __expf(-x)); }
;     DI void operator()(const Acc& acc, const pg8::Unit& u, int wr, int wc, int fr, int fq) const {
;     ...
;                     for (int m = 0; m < 4; ++m) { const int row = row0 + ai * 128 + m * 16; f32x4 v0 = acc[ai][bj][m][0], v1 = acc[ai][bj][m][1];
;                         if (seg == 0 || seg == 4) {
; #pragma unroll
;                             for (int j = 0; j < 4; ++j) { v0[j] = v0[j] * sigm(v0[j]); v1[j] = v1[j] * sigm(v1[j]); }
;                         } else if (seg == 1 || seg == 2) {
; #pragma unroll
;                             for (int j = 0; j < 4; ++j) { v0[j] = fmaxf(__logf(l0[j] + (1.0f - l0[j]) * sigm(v0[j])), -30.0f); v1[j] = fmaxf(__logf(l1[j] + (1.0f - l1[j]) * sigm(v1[j])), -30.0f); }
;                         }
;                         *(u32x4*)(dst + (size_t)row * 512 + col) = pk8(v0, v1); } }
.LBB0_522:
	v_cvt_pk_bf16_f32 v136, v136, v137
	v_cvt_pk_bf16_f32 v137, v138, v139
	v_cvt_pk_bf16_f32 v138, v140, v141
	v_cvt_pk_bf16_f32 v139, v142, v143
	v_lshl_add_u64 v[140:141], v[158:159], 0, v[162:163]
	s_and_b64 vcc, exec, s[42:43]
	s_mov_b64 s[2:3], -1
	global_store_dwordx4 v[140:141], v[136:139], off
	s_cbranch_vccnz .LBB0_526
	v_mov_b64_e32 v[142:143], v[82:83]
	v_mov_b64_e32 v[138:139], v[86:87]
	s_and_b64 vcc, exec, s[40:41]
	v_mov_b64_e32 v[140:141], v[80:81]
	v_mov_b64_e32 v[136:137], v[84:85]
	s_cbranch_vccnz .LBB0_525
	v_mul_f32_e32 v136, 0xbfb8aa3b, v84
	v_exp_f32_e32 v136, v136
	v_mul_f32_e32 v137, 0xbfb8aa3b, v80
	v_exp_f32_e32 v137, v137
	s_waitcnt vmcnt(3)
	v_sub_f32_e32 v138, 1.0, v132
	v_add_f32_e32 v136, 1.0, v136
	v_rcp_f32_e32 v136, v136
	s_mov_b32 s0, 0x800000
	v_add_f32_e32 v137, 1.0, v137
	v_rcp_f32_e32 v137, v137
	v_fma_f32 v136, v136, v138, v132
	v_mul_f32_e32 v139, 0xbfb8aa3b, v85
	v_exp_f32_e32 v139, v139
	v_log_f32_e32 v136, v136
	s_waitcnt vmcnt(2)
	v_sub_f32_e32 v138, 1.0, v128
	v_fma_f32 v137, v137, v138, v128
	v_add_f32_e32 v139, 1.0, v139
	v_rcp_f32_e32 v139, v139
	v_mul_f32_e32 v141, 0xbfb8aa3b, v86
	v_mul_f32_e32 v136, 0x3f317217, v136
	v_exp_f32_e32 v141, v141
	v_mul_f32_e32 v142, 0xbfb8aa3b, v82
	v_log_f32_e32 v137, v137
	v_add_f32_e32 v141, 1.0, v141
	v_rcp_f32_e32 v141, v141
	v_exp_f32_e32 v142, v142
	v_mul_f32_e32 v137, 0x3f317217, v137
	v_sub_f32_e32 v138, 1.0, v133
	v_fma_f32 v138, v139, v138, v133
	v_add_f32_e32 v142, 1.0, v142
	v_rcp_f32_e32 v142, v142
	v_mul_f32_e32 v139, 0xbfb8aa3b, v81
	v_log_f32_e32 v138, v138
	v_exp_f32_e32 v139, v139
	v_max_f32_e32 v140, 0xc1f00000, v137
	v_mul_f32_e32 v143, 0xbfb8aa3b, v87
	v_add_f32_e32 v139, 1.0, v139
	v_rcp_f32_e32 v139, v139
	v_exp_f32_e32 v143, v143
	v_mul_f32_e32 v155, 0xbfb8aa3b, v83
	v_mul_f32_e32 v137, 0x3f317217, v138
	v_sub_f32_e32 v138, 1.0, v129
	v_fma_f32 v138, v139, v138, v129
	v_add_f32_e32 v143, 1.0, v143
	v_rcp_f32_e32 v143, v143
	v_log_f32_e32 v138, v138
	v_exp_f32_e32 v155, v155
	s_nop 0
	v_add_f32_e32 v155, 1.0, v155
	v_rcp_f32_e32 v155, v155
	v_mul_f32_e32 v138, 0x3f317217, v138
	v_sub_f32_e32 v139, 1.0, v134
	v_fma_f32 v139, v141, v139, v134
	v_max_f32_e32 v136, 0xc1f00000, v136
	v_max_f32_e32 v137, 0xc1f00000, v137
	v_log_f32_e32 v139, v139
	v_max_f32_e32 v141, 0xc1f00000, v138
	s_nop 1
	v_mul_f32_e32 v138, 0x3f317217, v139
	v_sub_f32_e32 v139, 1.0, v130
	v_fma_f32 v139, v142, v139, v130
	s_nop 1
	v_log_f32_e32 v139, v139
	v_max_f32_e32 v138, 0xc1f00000, v138
	s_nop 1
	v_mul_f32_e32 v139, 0x3f317217, v139
	v_sub_f32_e32 v142, 1.0, v135
	v_fma_f32 v142, v143, v142, v135
	s_nop 1
	v_log_f32_e32 v143, v142
	v_max_f32_e32 v142, 0xc1f00000, v139
	s_nop 1
	v_mul_f32_e32 v139, 0x3f317217, v143
	v_sub_f32_e32 v143, 1.0, v131
	v_fma_f32 v143, v155, v143, v131
	s_nop 1
	v_log_f32_e32 v143, v143
	v_max_f32_e32 v139, 0xc1f00000, v139
	s_nop 1
	v_mul_f32_e32 v143, 0x3f317217, v143
	v_max_f32_e32 v143, 0xc1f00000, v143

; DI u32x4 pk8(f32x4 a, f32x4 b) { u32x4 r; r.x = pk2(a[0], a[1]); r.y = pk2(a[2], a[3]); r.z = pk2(b[0], b[1]); r.w = pk2(b[2], b[3]); return r; }
; DI float sigm(float x) { return __builtin_amdgcn_rcpf(1.0f + __expf(-x)); }
;     DI void operator()(const Acc& acc, const pg8::Unit& u, int wr, int wc, int fr, int fq) const {
;     ...
;                     for (int m = 0; m < 4; ++m) { const int row = row0 + ai * 128 + m * 16; f32x4 v0 = acc[ai][bj][m][0], v1 = acc[ai][bj][m][1];
;                         if (seg == 0 || seg == 4) {
; #pragma unroll
;                             for (int j = 0; j < 4; ++j) { v0[j] = v0[j] * sigm(v0[j]); v1[j] = v1[j] * sigm(v1[j]); }
;                         } else if (seg == 1 || seg == 2) {
; #pragma unroll
;                             for (int j = 0; j < 4; ++j) { v0[j] = fmaxf(__logf(l0[j] + (1.0f - l0[j]) * sigm(v0[j])), -30.0f); v1[j] = fmaxf(__logf(l1[j] + (1.0f - l1[j]) * sigm(v1[j])), -30.0f); }
;                         }
;                         *(u32x4*)(dst + (size_t)row * 512 + col) = pk8(v0, v1); } }
.LBB0_528:
	v_cvt_pk_bf16_f32 v136, v136, v137
	v_cvt_pk_bf16_f32 v137, v138, v139
	v_cvt_pk_bf16_f32 v138, v140, v141
	v_cvt_pk_bf16_f32 v139, v142, v143
	v_lshl_add_u64 v[140:141], v[158:159], 0, v[170:171]
	s_and_b64 vcc, exec, s[42:43]
	s_mov_b64 s[2:3], -1
	global_store_dwordx4 v[140:141], v[136:139], off
	s_cbranch_vccnz .LBB0_532
	v_mov_b64_e32 v[142:143], v[66:67]
	v_mov_b64_e32 v[138:139], v[70:71]
	s_and_b64 vcc, exec, s[40:41]
	v_mov_b64_e32 v[140:141], v[64:65]
	v_mov_b64_e32 v[136:137], v[68:69]
	s_cbranch_vccnz .LBB0_531
	v_mul_f32_e32 v136, 0xbfb8aa3b, v68
	v_exp_f32_e32 v136, v136
	v_mul_f32_e32 v137, 0xbfb8aa3b, v64
	v_exp_f32_e32 v137, v137
	s_waitcnt vmcnt(4)
	v_sub_f32_e32 v138, 1.0, v132
	v_add_f32_e32 v136, 1.0, v136
	v_rcp_f32_e32 v136, v136
	s_mov_b32 s0, 0x800000
	v_add_f32_e32 v137, 1.0, v137
	v_rcp_f32_e32 v137, v137
	v_fma_f32 v136, v136, v138, v132
	v_mul_f32_e32 v139, 0xbfb8aa3b, v69
	v_exp_f32_e32 v139, v139
	v_log_f32_e32 v136, v136
	s_waitcnt vmcnt(3)
	v_sub_f32_e32 v138, 1.0, v128
	v_fma_f32 v137, v137, v138, v128
	v_add_f32_e32 v139, 1.0, v139
	v_rcp_f32_e32 v139, v139
	v_mul_f32_e32 v141, 0xbfb8aa3b, v70
	v_mul_f32_e32 v136, 0x3f317217, v136
	v_exp_f32_e32 v141, v141
	v_mul_f32_e32 v142, 0xbfb8aa3b, v66
	v_log_f32_e32 v137, v137
	v_add_f32_e32 v141, 1.0, v141
	v_rcp_f32_e32 v141, v141
	v_exp_f32_e32 v142, v142
	v_mul_f32_e32 v137, 0x3f317217, v137
	v_sub_f32_e32 v138, 1.0, v133
	v_fma_f32 v138, v139, v138, v133
	v_add_f32_e32 v142, 1.0, v142
	v_rcp_f32_e32 v142, v142
	v_mul_f32_e32 v139, 0xbfb8aa3b, v65
	v_log_f32_e32 v138, v138
	v_exp_f32_e32 v139, v139
	v_max_f32_e32 v140, 0xc1f00000, v137
	v_mul_f32_e32 v143, 0xbfb8aa3b, v71
	v_add_f32_e32 v139, 1.0, v139
	v_rcp_f32_e32 v139, v139
	v_exp_f32_e32 v143, v143
	v_mul_f32_e32 v155, 0xbfb8aa3b, v67
	v_mul_f32_e32 v137, 0x3f317217, v138
	v_sub_f32_e32 v138, 1.0, v129
	v_fma_f32 v138, v139, v138, v129
	v_add_f32_e32 v143, 1.0, v143
	v_rcp_f32_e32 v143, v143
	v_log_f32_e32 v138, v138
	v_exp_f32_e32 v155, v155
	s_nop 0
	v_add_f32_e32 v155, 1.0, v155
	v_rcp_f32_e32 v155, v155
	v_mul_f32_e32 v138, 0x3f317217, v138
	v_sub_f32_e32 v139, 1.0, v134
	v_fma_f32 v139, v141, v139, v134
	v_max_f32_e32 v136, 0xc1f00000, v136
	v_max_f32_e32 v137, 0xc1f00000, v137
	v_log_f32_e32 v139, v139
	v_max_f32_e32 v141, 0xc1f00000, v138
	s_nop 1
	v_mul_f32_e32 v138, 0x3f317217, v139
	v_sub_f32_e32 v139, 1.0, v130
	v_fma_f32 v139, v142, v139, v130
	s_nop 1
	v_log_f32_e32 v139, v139
	v_max_f32_e32 v138, 0xc1f00000, v138
	s_nop 1
	v_mul_f32_e32 v139, 0x3f317217, v139
	v_sub_f32_e32 v142, 1.0, v135
	v_fma_f32 v142, v143, v142, v135
	s_nop 1
	v_log_f32_e32 v143, v142
	v_max_f32_e32 v142, 0xc1f00000, v139
	s_nop 1
	v_mul_f32_e32 v139, 0x3f317217, v143
	v_sub_f32_e32 v143, 1.0, v131
	v_fma_f32 v143, v155, v143, v131
	s_nop 1
	v_log_f32_e32 v143, v143
	v_max_f32_e32 v139, 0xc1f00000, v139
	s_nop 1
	v_mul_f32_e32 v143, 0x3f317217, v143
	v_max_f32_e32 v143, 0xc1f00000, v143

; DI u32x4 pk8(f32x4 a, f32x4 b) { u32x4 r; r.x = pk2(a[0], a[1]); r.y = pk2(a[2], a[3]); r.z = pk2(b[0], b[1]); r.w = pk2(b[2], b[3]); return r; }
; DI float sigm(float x) { return __builtin_amdgcn_rcpf(1.0f + __expf(-x)); }
;     DI void operator()(const Acc& acc, const pg8::Unit& u, int wr, int wc, int fr, int fq) const {
;     ...
;                     for (int m = 0; m < 4; ++m) { const int row = row0 + ai * 128 + m * 16; f32x4 v0 = acc[ai][bj][m][0], v1 = acc[ai][bj][m][1];
;                         if (seg == 0 || seg == 4) {
; #pragma unroll
;                             for (int j = 0; j < 4; ++j) { v0[j] = v0[j] * sigm(v0[j]); v1[j] = v1[j] * sigm(v1[j]); }
;                         } else if (seg == 1 || seg == 2) {
; #pragma unroll
;                             for (int j = 0; j < 4; ++j) { v0[j] = fmaxf(__logf(l0[j] + (1.0f - l0[j]) * sigm(v0[j])), -30.0f); v1[j] = fmaxf(__logf(l1[j] + (1.0f - l1[j]) * sigm(v1[j])), -30.0f); }
;                         }
;                         *(u32x4*)(dst + (size_t)row * 512 + col) = pk8(v0, v1); } }
.LBB0_534:
	v_cvt_pk_bf16_f32 v136, v136, v137
	v_cvt_pk_bf16_f32 v137, v138, v139
	v_cvt_pk_bf16_f32 v138, v140, v141
	v_cvt_pk_bf16_f32 v139, v142, v143
	v_lshl_add_u64 v[140:141], v[158:159], 0, v[172:173]
	s_and_b64 vcc, exec, s[42:43]
	s_mov_b64 s[2:3], -1
	global_store_dwordx4 v[140:141], v[136:139], off
	s_cbranch_vccnz .LBB0_538
	v_mov_b64_e32 v[142:143], v[50:51]
	v_mov_b64_e32 v[138:139], v[54:55]
	s_and_b64 vcc, exec, s[40:41]
	v_mov_b64_e32 v[140:141], v[48:49]
	v_mov_b64_e32 v[136:137], v[52:53]
	s_cbranch_vccnz .LBB0_537
	v_mul_f32_e32 v136, 0xbfb8aa3b, v52
	v_exp_f32_e32 v136, v136
	v_mul_f32_e32 v137, 0xbfb8aa3b, v48
	v_exp_f32_e32 v137, v137
	s_waitcnt vmcnt(5)
	v_sub_f32_e32 v138, 1.0, v132
	v_add_f32_e32 v136, 1.0, v136
	v_rcp_f32_e32 v136, v136
	s_mov_b32 s0, 0x800000
	v_add_f32_e32 v137, 1.0, v137
	v_rcp_f32_e32 v137, v137
	v_fma_f32 v136, v136, v138, v132
	v_mul_f32_e32 v139, 0xbfb8aa3b, v53
	v_exp_f32_e32 v139, v139
	v_log_f32_e32 v136, v136
	s_waitcnt vmcnt(4)
	v_sub_f32_e32 v138, 1.0, v128
	v_fma_f32 v137, v137, v138, v128
	v_add_f32_e32 v139, 1.0, v139
	v_rcp_f32_e32 v139, v139
	v_mul_f32_e32 v141, 0xbfb8aa3b, v54
	v_mul_f32_e32 v136, 0x3f317217, v136
	v_exp_f32_e32 v141, v141
	v_mul_f32_e32 v142, 0xbfb8aa3b, v50
	v_log_f32_e32 v137, v137
	v_add_f32_e32 v141, 1.0, v141
	v_rcp_f32_e32 v141, v141
	v_exp_f32_e32 v142, v142
	v_mul_f32_e32 v137, 0x3f317217, v137
	v_sub_f32_e32 v138, 1.0, v133
	v_fma_f32 v138, v139, v138, v133
	v_add_f32_e32 v142, 1.0, v142
	v_rcp_f32_e32 v142, v142
	v_mul_f32_e32 v139, 0xbfb8aa3b, v49
	v_log_f32_e32 v138, v138
	v_exp_f32_e32 v139, v139
	v_max_f32_e32 v140, 0xc1f00000, v137
	v_mul_f32_e32 v143, 0xbfb8aa3b, v55
	v_add_f32_e32 v139, 1.0, v139
	v_rcp_f32_e32 v139, v139
	v_exp_f32_e32 v143, v143
	v_mul_f32_e32 v155, 0xbfb8aa3b, v51
	v_mul_f32_e32 v137, 0x3f317217, v138
	v_sub_f32_e32 v138, 1.0, v129
	v_fma_f32 v138, v139, v138, v129
	v_add_f32_e32 v143, 1.0, v143
	v_rcp_f32_e32 v143, v143
	v_log_f32_e32 v138, v138
	v_exp_f32_e32 v155, v155
	s_nop 0
	v_add_f32_e32 v155, 1.0, v155
	v_rcp_f32_e32 v155, v155
	v_mul_f32_e32 v138, 0x3f317217, v138
	v_sub_f32_e32 v139, 1.0, v134
	v_fma_f32 v139, v141, v139, v134
	v_max_f32_e32 v136, 0xc1f00000, v136
	v_max_f32_e32 v137, 0xc1f00000, v137
	v_log_f32_e32 v139, v139
	v_max_f32_e32 v141, 0xc1f00000, v138
	s_nop 1
	v_mul_f32_e32 v138, 0x3f317217, v139
	v_sub_f32_e32 v139, 1.0, v130
	v_fma_f32 v139, v142, v139, v130
	s_nop 1
	v_log_f32_e32 v139, v139
	v_max_f32_e32 v138, 0xc1f00000, v138
	s_nop 1
	v_mul_f32_e32 v139, 0x3f317217, v139
	v_sub_f32_e32 v142, 1.0, v135
	v_fma_f32 v142, v143, v142, v135
	s_nop 1
	v_log_f32_e32 v143, v142
	v_max_f32_e32 v142, 0xc1f00000, v139
	s_nop 1
	v_mul_f32_e32 v139, 0x3f317217, v143
	v_sub_f32_e32 v143, 1.0, v131
	v_fma_f32 v143, v155, v143, v131
	s_nop 1
	v_log_f32_e32 v143, v143
	v_max_f32_e32 v139, 0xc1f00000, v139
	s_nop 1
	v_mul_f32_e32 v143, 0x3f317217, v143
	v_max_f32_e32 v143, 0xc1f00000, v143

; DI u32x4 pk8(f32x4 a, f32x4 b) { u32x4 r; r.x = pk2(a[0], a[1]); r.y = pk2(a[2], a[3]); r.z = pk2(b[0], b[1]); r.w = pk2(b[2], b[3]); return r; }
; DI float sigm(float x) { return __builtin_amdgcn_rcpf(1.0f + __expf(-x)); }
;     DI void operator()(const Acc& acc, const pg8::Unit& u, int wr, int wc, int fr, int fq) const {
;     ...
;                     for (int m = 0; m < 4; ++m) { const int row = row0 + ai * 128 + m * 16; f32x4 v0 = acc[ai][bj][m][0], v1 = acc[ai][bj][m][1];
;                         if (seg == 0 || seg == 4) {
; #pragma unroll
;                             for (int j = 0; j < 4; ++j) { v0[j] = v0[j] * sigm(v0[j]); v1[j] = v1[j] * sigm(v1[j]); }
;                         } else if (seg == 1 || seg == 2) {
; #pragma unroll
;                             for (int j = 0; j < 4; ++j) { v0[j] = fmaxf(__logf(l0[j] + (1.0f - l0[j]) * sigm(v0[j])), -30.0f); v1[j] = fmaxf(__logf(l1[j] + (1.0f - l1[j]) * sigm(v1[j])), -30.0f); }
;                         }
;                         *(u32x4*)(dst + (size_t)row * 512 + col) = pk8(v0, v1); } }
.LBB0_540:
	v_cvt_pk_bf16_f32 v136, v136, v137
	v_cvt_pk_bf16_f32 v137, v138, v139
	v_cvt_pk_bf16_f32 v138, v140, v141
	v_cvt_pk_bf16_f32 v139, v142, v143
	v_lshl_add_u64 v[140:141], v[158:159], 0, v[174:175]
	s_and_b64 vcc, exec, s[42:43]
	s_mov_b64 s[2:3], -1
	global_store_dwordx4 v[140:141], v[136:139], off
	s_cbranch_vccnz .LBB0_544
	v_mov_b64_e32 v[142:143], v[34:35]
	v_mov_b64_e32 v[138:139], v[38:39]
	s_and_b64 vcc, exec, s[40:41]
	v_mov_b64_e32 v[140:141], v[32:33]
	v_mov_b64_e32 v[136:137], v[36:37]
	s_cbranch_vccnz .LBB0_543
	v_mul_f32_e32 v136, 0xbfb8aa3b, v36
	v_exp_f32_e32 v136, v136
	v_mul_f32_e32 v137, 0xbfb8aa3b, v32
	v_exp_f32_e32 v137, v137
	s_waitcnt vmcnt(6)
	v_sub_f32_e32 v138, 1.0, v132
	v_add_f32_e32 v136, 1.0, v136
	v_rcp_f32_e32 v136, v136
	s_mov_b32 s0, 0x800000
	v_add_f32_e32 v137, 1.0, v137
	v_rcp_f32_e32 v137, v137
	v_fma_f32 v136, v136, v138, v132
	v_mul_f32_e32 v139, 0xbfb8aa3b, v37
	v_exp_f32_e32 v139, v139
	v_log_f32_e32 v136, v136
	s_waitcnt vmcnt(5)
	v_sub_f32_e32 v138, 1.0, v128
	v_fma_f32 v137, v137, v138, v128
	v_add_f32_e32 v139, 1.0, v139
	v_rcp_f32_e32 v139, v139
	v_mul_f32_e32 v141, 0xbfb8aa3b, v38
	v_mul_f32_e32 v136, 0x3f317217, v136
	v_exp_f32_e32 v141, v141
	v_mul_f32_e32 v142, 0xbfb8aa3b, v34
	v_log_f32_e32 v137, v137
	v_add_f32_e32 v141, 1.0, v141
	v_rcp_f32_e32 v141, v141
	v_exp_f32_e32 v142, v142
	v_mul_f32_e32 v137, 0x3f317217, v137
	v_sub_f32_e32 v138, 1.0, v133
	v_fma_f32 v138, v139, v138, v133
	v_add_f32_e32 v142, 1.0, v142
	v_rcp_f32_e32 v142, v142
	v_mul_f32_e32 v139, 0xbfb8aa3b, v33
	v_log_f32_e32 v138, v138
	v_exp_f32_e32 v139, v139
	v_max_f32_e32 v140, 0xc1f00000, v137
	v_mul_f32_e32 v143, 0xbfb8aa3b, v39
	v_add_f32_e32 v139, 1.0, v139
	v_rcp_f32_e32 v139, v139
	v_exp_f32_e32 v143, v143
	v_mul_f32_e32 v155, 0xbfb8aa3b, v35
	v_mul_f32_e32 v137, 0x3f317217, v138
	v_sub_f32_e32 v138, 1.0, v129
	v_fma_f32 v138, v139, v138, v129
	v_add_f32_e32 v143, 1.0, v143
	v_rcp_f32_e32 v143, v143
	v_log_f32_e32 v138, v138
	v_exp_f32_e32 v155, v155
	s_nop 0
	v_add_f32_e32 v155, 1.0, v155
	v_rcp_f32_e32 v155, v155
	v_mul_f32_e32 v138, 0x3f317217, v138
	v_sub_f32_e32 v139, 1.0, v134
	v_fma_f32 v139, v141, v139, v134
	v_max_f32_e32 v136, 0xc1f00000, v136
	v_max_f32_e32 v137, 0xc1f00000, v137
	v_log_f32_e32 v139, v139
	v_max_f32_e32 v141, 0xc1f00000, v138
	s_nop 1
	v_mul_f32_e32 v138, 0x3f317217, v139
	v_sub_f32_e32 v139, 1.0, v130
	v_fma_f32 v139, v142, v139, v130
	s_nop 1
	v_log_f32_e32 v139, v139
	v_max_f32_e32 v138, 0xc1f00000, v138
	s_nop 1
	v_mul_f32_e32 v139, 0x3f317217, v139
	v_sub_f32_e32 v142, 1.0, v135
	v_fma_f32 v142, v143, v142, v135
	s_nop 1
	v_log_f32_e32 v143, v142
	v_max_f32_e32 v142, 0xc1f00000, v139
	s_nop 1
	v_mul_f32_e32 v139, 0x3f317217, v143
	v_sub_f32_e32 v143, 1.0, v131
	v_fma_f32 v143, v155, v143, v131
	s_nop 1
	v_log_f32_e32 v143, v143
	v_max_f32_e32 v139, 0xc1f00000, v139
	s_nop 1
	v_mul_f32_e32 v143, 0x3f317217, v143
	v_max_f32_e32 v143, 0xc1f00000, v143

; DI u32x4 pk8(f32x4 a, f32x4 b) { u32x4 r; r.x = pk2(a[0], a[1]); r.y = pk2(a[2], a[3]); r.z = pk2(b[0], b[1]); r.w = pk2(b[2], b[3]); return r; }
; DI float sigm(float x) { return __builtin_amdgcn_rcpf(1.0f + __expf(-x)); }
;     DI void operator()(const Acc& acc, const pg8::Unit& u, int wr, int wc, int fr, int fq) const {
;     ...
;                     for (int m = 0; m < 4; ++m) { const int row = row0 + ai * 128 + m * 16; f32x4 v0 = acc[ai][bj][m][0], v1 = acc[ai][bj][m][1];
;                         if (seg == 0 || seg == 4) {
; #pragma unroll
;                             for (int j = 0; j < 4; ++j) { v0[j] = v0[j] * sigm(v0[j]); v1[j] = v1[j] * sigm(v1[j]); }
;                         } else if (seg == 1 || seg == 2) {
; #pragma unroll
;                             for (int j = 0; j < 4; ++j) { v0[j] = fmaxf(__logf(l0[j] + (1.0f - l0[j]) * sigm(v0[j])), -30.0f); v1[j] = fmaxf(__logf(l1[j] + (1.0f - l1[j]) * sigm(v1[j])), -30.0f); }
;                         }
;                         *(u32x4*)(dst + (size_t)row * 512 + col) = pk8(v0, v1); } }
.LBB0_546:
	v_cvt_pk_bf16_f32 v136, v136, v137
	v_cvt_pk_bf16_f32 v137, v138, v139
	v_cvt_pk_bf16_f32 v138, v140, v141
	v_cvt_pk_bf16_f32 v139, v142, v143
	v_lshl_add_u64 v[140:141], v[158:159], 0, v[176:177]
	s_and_b64 vcc, exec, s[42:43]
	s_mov_b64 s[2:3], -1
	global_store_dwordx4 v[140:141], v[136:139], off
	s_cbranch_vccnz .LBB0_550
	v_mov_b64_e32 v[142:143], v[18:19]
	v_mov_b64_e32 v[138:139], v[22:23]
	s_and_b64 vcc, exec, s[40:41]
	v_mov_b64_e32 v[140:141], v[16:17]
	v_mov_b64_e32 v[136:137], v[20:21]
	s_cbranch_vccnz .LBB0_549
	v_mul_f32_e32 v136, 0xbfb8aa3b, v20
	v_exp_f32_e32 v136, v136
	v_mul_f32_e32 v137, 0xbfb8aa3b, v16
	v_exp_f32_e32 v137, v137
	s_waitcnt vmcnt(7)
	v_sub_f32_e32 v138, 1.0, v132
	v_add_f32_e32 v136, 1.0, v136
	v_rcp_f32_e32 v136, v136
	s_mov_b32 s0, 0x800000
	v_add_f32_e32 v137, 1.0, v137
	v_rcp_f32_e32 v137, v137
	v_fma_f32 v136, v136, v138, v132
	v_mul_f32_e32 v139, 0xbfb8aa3b, v21
	v_exp_f32_e32 v139, v139
	v_log_f32_e32 v136, v136
	s_waitcnt vmcnt(6)
	v_sub_f32_e32 v138, 1.0, v128
	v_fma_f32 v137, v137, v138, v128
	v_add_f32_e32 v139, 1.0, v139
	v_rcp_f32_e32 v139, v139
	v_mul_f32_e32 v141, 0xbfb8aa3b, v22
	v_mul_f32_e32 v136, 0x3f317217, v136
	v_exp_f32_e32 v141, v141
	v_mul_f32_e32 v142, 0xbfb8aa3b, v18
	v_log_f32_e32 v137, v137
	v_add_f32_e32 v141, 1.0, v141
	v_rcp_f32_e32 v141, v141
	v_exp_f32_e32 v142, v142
	v_mul_f32_e32 v137, 0x3f317217, v137
	v_sub_f32_e32 v138, 1.0, v133
	v_fma_f32 v138, v139, v138, v133
	v_add_f32_e32 v142, 1.0, v142
	v_rcp_f32_e32 v142, v142
	v_mul_f32_e32 v139, 0xbfb8aa3b, v17
	v_log_f32_e32 v138, v138
	v_exp_f32_e32 v139, v139
	v_max_f32_e32 v140, 0xc1f00000, v137
	v_mul_f32_e32 v143, 0xbfb8aa3b, v23
	v_add_f32_e32 v139, 1.0, v139
	v_rcp_f32_e32 v139, v139
	v_exp_f32_e32 v143, v143
	v_mul_f32_e32 v155, 0xbfb8aa3b, v19
	v_mul_f32_e32 v137, 0x3f317217, v138
	v_sub_f32_e32 v138, 1.0, v129
	v_fma_f32 v138, v139, v138, v129
	v_add_f32_e32 v143, 1.0, v143
	v_rcp_f32_e32 v143, v143
	v_log_f32_e32 v138, v138
	v_exp_f32_e32 v155, v155
	s_nop 0
	v_add_f32_e32 v155, 1.0, v155
	v_rcp_f32_e32 v155, v155
	v_mul_f32_e32 v138, 0x3f317217, v138
	v_sub_f32_e32 v139, 1.0, v134
	v_fma_f32 v139, v141, v139, v134
	v_max_f32_e32 v136, 0xc1f00000, v136
	v_max_f32_e32 v137, 0xc1f00000, v137
	v_log_f32_e32 v139, v139
	v_max_f32_e32 v141, 0xc1f00000, v138
	s_nop 1
	v_mul_f32_e32 v138, 0x3f317217, v139
	v_sub_f32_e32 v139, 1.0, v130
	v_fma_f32 v139, v142, v139, v130
	s_nop 1
	v_log_f32_e32 v139, v139
	v_max_f32_e32 v138, 0xc1f00000, v138
	s_nop 1
	v_mul_f32_e32 v139, 0x3f317217, v139
	v_sub_f32_e32 v142, 1.0, v135
	v_fma_f32 v142, v143, v142, v135
	s_nop 1
	v_log_f32_e32 v143, v142
	v_max_f32_e32 v142, 0xc1f00000, v139
	s_nop 1
	v_mul_f32_e32 v139, 0x3f317217, v143
	v_sub_f32_e32 v143, 1.0, v131
	v_fma_f32 v143, v155, v143, v131
	s_nop 1
	v_log_f32_e32 v143, v143
	v_max_f32_e32 v139, 0xc1f00000, v139
	s_nop 1
	v_mul_f32_e32 v143, 0x3f317217, v143
	v_max_f32_e32 v143, 0xc1f00000, v143

; DI u32x4 pk8(f32x4 a, f32x4 b) { u32x4 r; r.x = pk2(a[0], a[1]); r.y = pk2(a[2], a[3]); r.z = pk2(b[0], b[1]); r.w = pk2(b[2], b[3]); return r; }
; DI float sigm(float x) { return __builtin_amdgcn_rcpf(1.0f + __expf(-x)); }
;     DI void operator()(const Acc& acc, const pg8::Unit& u, int wr, int wc, int fr, int fq) const {
;     ...
;                     for (int m = 0; m < 4; ++m) { const int row = row0 + ai * 128 + m * 16; f32x4 v0 = acc[ai][bj][m][0], v1 = acc[ai][bj][m][1];
;                         if (seg == 0 || seg == 4) {
; #pragma unroll
;                             for (int j = 0; j < 4; ++j) { v0[j] = v0[j] * sigm(v0[j]); v1[j] = v1[j] * sigm(v1[j]); }
;                         } else if (seg == 1 || seg == 2) {
; #pragma unroll
;                             for (int j = 0; j < 4; ++j) { v0[j] = fmaxf(__logf(l0[j] + (1.0f - l0[j]) * sigm(v0[j])), -30.0f); v1[j] = fmaxf(__logf(l1[j] + (1.0f - l1[j]) * sigm(v1[j])), -30.0f); }
;                         }
;                         *(u32x4*)(dst + (size_t)row * 512 + col) = pk8(v0, v1); } }
.LBB0_552:
	v_cvt_pk_bf16_f32 v136, v136, v137
	v_cvt_pk_bf16_f32 v137, v138, v139
	v_cvt_pk_bf16_f32 v138, v140, v141
	v_cvt_pk_bf16_f32 v139, v142, v143
	v_lshl_add_u64 v[140:141], v[158:159], 0, v[178:179]
	s_and_b64 vcc, exec, s[42:43]
	s_mov_b64 s[2:3], -1
	global_store_dwordx4 v[140:141], v[136:139], off
	s_cbranch_vccnz .LBB0_556
	v_mov_b64_e32 v[142:143], v[2:3]
	v_mov_b64_e32 v[138:139], v[6:7]
	s_and_b64 vcc, exec, s[40:41]
	v_mov_b64_e32 v[140:141], v[0:1]
	v_mov_b64_e32 v[136:137], v[4:5]
	s_cbranch_vccnz .LBB0_555
	v_mul_f32_e32 v137, 0xbfb8aa3b, v4
	v_exp_f32_e32 v137, v137
	s_waitcnt vmcnt(8)
	v_sub_f32_e32 v136, 1.0, v132
	s_mov_b32 s0, 0x800000
	v_add_f32_e32 v137, 1.0, v137
	v_rcp_f32_e32 v137, v137
	s_nop 0
	v_fmac_f32_e32 v132, v137, v136
	v_mul_f32_e32 v137, 0xbfb8aa3b, v0
	v_exp_f32_e32 v137, v137
	v_log_f32_e32 v132, v132
	v_add_f32_e32 v137, 1.0, v137
	v_rcp_f32_e32 v137, v137
	s_nop 1
	v_mul_f32_e32 v132, 0x3f317217, v132
	v_max_f32_e32 v136, 0xc1f00000, v132
	s_waitcnt vmcnt(7)
	v_sub_f32_e32 v132, 1.0, v128
	v_fmac_f32_e32 v128, v137, v132
	s_nop 1
	v_log_f32_e32 v128, v128
	s_nop 0
	s_nop 1
	v_mul_f32_e32 v128, 0x3f317217, v128
	v_mul_f32_e32 v132, 0xbfb8aa3b, v5
	v_exp_f32_e32 v132, v132
	v_max_f32_e32 v140, 0xc1f00000, v128
	v_sub_f32_e32 v128, 1.0, v133
	v_add_f32_e32 v132, 1.0, v132
	v_rcp_f32_e32 v132, v132
	s_nop 0
	v_fmac_f32_e32 v133, v132, v128
	s_nop 1
	v_log_f32_e32 v128, v133
	s_nop 0
	s_nop 1
	v_mul_f32_e32 v128, 0x3f317217, v128
	v_mul_f32_e32 v132, 0xbfb8aa3b, v1
	v_exp_f32_e32 v132, v132
	v_max_f32_e32 v137, 0xc1f00000, v128
	v_sub_f32_e32 v128, 1.0, v129
	v_add_f32_e32 v132, 1.0, v132
	v_rcp_f32_e32 v132, v132
	s_nop 0
	v_fmac_f32_e32 v129, v132, v128
	s_nop 1
	v_log_f32_e32 v128, v129
	s_nop 0
	s_nop 1
	v_mul_f32_e32 v128, 0x3f317217, v128
	v_mul_f32_e32 v129, 0xbfb8aa3b, v6
	v_exp_f32_e32 v129, v129
	v_max_f32_e32 v141, 0xc1f00000, v128
	v_sub_f32_e32 v128, 1.0, v134
	v_add_f32_e32 v129, 1.0, v129
	v_rcp_f32_e32 v129, v129
	s_nop 0
	v_fmac_f32_e32 v134, v129, v128
	s_nop 1
	v_log_f32_e32 v128, v134
	s_nop 0
	s_nop 1
	v_mul_f32_e32 v128, 0x3f317217, v128
	v_mul_f32_e32 v129, 0xbfb8aa3b, v2
	v_exp_f32_e32 v129, v129
	v_max_f32_e32 v138, 0xc1f00000, v128
	v_sub_f32_e32 v128, 1.0, v130
	v_add_f32_e32 v129, 1.0, v129
	v_rcp_f32_e32 v129, v129
	s_nop 0
	v_fmac_f32_e32 v130, v129, v128
	s_nop 1
	v_log_f32_e32 v128, v130
	s_nop 0
	s_nop 1
	v_mul_f32_e32 v128, 0x3f317217, v128
	v_mul_f32_e32 v129, 0xbfb8aa3b, v7
	v_exp_f32_e32 v129, v129
	v_max_f32_e32 v142, 0xc1f00000, v128
	v_sub_f32_e32 v128, 1.0, v135
	v_add_f32_e32 v129, 1.0, v129
	v_rcp_f32_e32 v129, v129
	s_nop 0
	v_fmac_f32_e32 v135, v129, v128
	s_nop 1
	v_log_f32_e32 v128, v135
	s_nop 0
	s_nop 1
	v_mul_f32_e32 v128, 0x3f317217, v128
	v_mul_f32_e32 v129, 0xbfb8aa3b, v3
	v_exp_f32_e32 v129, v129
	v_max_f32_e32 v139, 0xc1f00000, v128
	v_sub_f32_e32 v128, 1.0, v131
	v_add_f32_e32 v129, 1.0, v129
	v_rcp_f32_e32 v129, v129
	s_nop 0
	v_fmac_f32_e32 v131, v129, v128
	s_nop 1
	v_log_f32_e32 v128, v131
	s_nop 0
	s_nop 1
	v_mul_f32_e32 v128, 0x3f317217, v128
	v_max_f32_e32 v143, 0xc1f00000, v128

; DI float blo(unsigned w) { return __uint_as_float(w << 16); }
; DI float bhi(unsigned w) { return __uint_as_float(w & 0xffff0000u); }
; DI u32x4 pk8(f32x4 a, f32x4 b) { u32x4 r; r.x = pk2(a[0], a[1]); r.y = pk2(a[2], a[3]); r.z = pk2(b[0], b[1]); r.w = pk2(b[2], b[3]); return r; }
;     DI void operator()(const Acc& acc, const pg8::Unit& u, int wr, int wc, int fr, int fq) const {
;     ...
;             for (int m = 0; m < 4; ++m) { const int row = row0 + ai * 128 + m * 16; float ss = 0.f;
; #pragma unroll
;                 for (int bj = 0; bj < 2; ++bj) { f32x4 v0 = acc[ai][bj][m][0], v1 = acc[ai][bj][m][1]; const size_t off = (size_t)row * 1024 + c0 + bj * 128;
;                     if (gate) { const u32x4 gw = *(const u32x4*)(gate + off);
;                         v0[0] *= blo(gw.x); v0[1] *= bhi(gw.x); v0[2] *= blo(gw.y); v0[3] *= bhi(gw.y); v1[0] *= blo(gw.z); v1[1] *= bhi(gw.z); v1[2] *= blo(gw.w); v1[3] *= bhi(gw.w); }
;                     *(u32x4*)(t + off) = pk8(v0, v1);
;                     ss += v0[0] * v0[0] + v0[1] * v0[1] + v0[2] * v0[2] + v0[3] * v0[3] + v1[0] * v1[0] + v1[1] * v1[1] + v1[2] * v1[2] + v1[3] * v1[3]; }
;                 ss += __shfl_xor(ss, 16); ss += __shfl_xor(ss, 32);
;                 if (fq == 0) ssq[row * 16 + u.pn * 4 + wc] = ss;
.LBB0_1671:
	s_lshl_b32 s0, s89, 8
	v_mov_b32_e32 v138, v150
	v_mov_b32_e32 v141, v149
	s_add_i32 s0, s0, s60
	v_add_u32_e32 v153, 64, v148
	v_cmp_lt_i32_e32 vcc, v146, v153
	v_add_u32_e32 v140, s0, v138
	s_lshl_b32 s0, s88, 8
	s_or_b32 s0, s0, s61
	v_cndmask_b32_e32 v154, v184, v146, vcc
	v_cmp_lt_i32_e32 vcc, v147, v153
	v_lshl_add_u32 v138, v141, 3, s0
	v_ashrrev_i32_e32 v139, 31, v138
	v_cndmask_b32_e32 v153, v184, v147, vcc
	v_cmp_eq_u32_e32 vcc, 0, v141
	v_ashrrev_i32_e32 v141, 31, v140
	v_lshlrev_b64 v[156:157], 10, v[140:141]
	v_lshl_add_u64 v[156:157], v[156:157], 0, v[138:139]
	v_readlane_b32 s4, v237, 44
	v_lshlrev_b64 v[160:161], 1, v[156:157]
	v_readlane_b32 s5, v237, 45
	v_lshlrev_b32_e32 v154, 2, v154
	v_lshlrev_b32_e32 v153, 2, v153
	v_lshl_add_u64 v[162:163], s[4:5], 0, v[160:161]
	s_mov_b32 s100, 0x8000
	s_mov_b32 s101, 0
	s_mov_b32 s98, 0x28000
	s_mov_b32 s99, 0
	global_load_dwordx4 v[172:175], v[162:163], off offset:256
	v_lshl_add_u64 v[252:253], v[162:163], 0, s[100:101]
	global_load_dwordx4 v[176:179], v[252:253], off
	global_load_dwordx4 v[188:191], v[252:253], off offset:256
	v_lshl_add_u64 v[252:253], v[252:253], 0, s[100:101]
	global_load_dwordx4 v[192:195], v[252:253], off
	global_load_dwordx4 v[196:199], v[252:253], off offset:256
	v_lshl_add_u64 v[252:253], v[252:253], 0, s[100:101]
	global_load_dwordx4 v[200:203], v[252:253], off
	global_load_dwordx4 v[204:207], v[252:253], off offset:256
	v_lshl_add_u64 v[252:253], v[252:253], 0, s[98:99]
	global_load_dwordx4 v[208:211], v[252:253], off
	global_load_dwordx4 v[212:215], v[252:253], off offset:256
	v_lshl_add_u64 v[252:253], v[252:253], 0, s[100:101]
	global_load_dwordx4 v[216:219], v[252:253], off
	global_load_dwordx4 v[220:223], v[252:253], off offset:256
	v_lshl_add_u64 v[252:253], v[252:253], 0, s[100:101]
	global_load_dwordx4 v[224:227], v[252:253], off
	global_load_dwordx4 v[240:243], v[252:253], off offset:256
	v_lshl_add_u64 v[252:253], v[252:253], 0, s[100:101]
	global_load_dwordx4 v[244:247], v[252:253], off
	global_load_dwordx4 v[248:251], v[252:253], off offset:256
	global_load_dwordx4 v[156:159], v[162:163], off
	v_lshl_add_u64 v[160:161], s[2:3], 0, v[160:161]
	s_lshl_b32 s0, s88, 2
	s_or_b32 s42, s0, s58
	s_waitcnt vmcnt(0)
	v_lshlrev_b32_e32 v170, 16, v156
	v_and_b32_e32 v171, 0xffff0000, v156
	v_lshlrev_b32_e32 v156, 16, v157
	v_and_b32_e32 v157, 0xffff0000, v157
	v_pk_mul_f32 v[126:127], v[126:127], v[156:157]
	v_lshlrev_b32_e32 v156, 16, v158
	v_and_b32_e32 v157, 0xffff0000, v158
	v_pk_mul_f32 v[156:157], v[120:121], v[156:157]
	v_lshlrev_b32_e32 v120, 16, v159
	v_and_b32_e32 v121, 0xffff0000, v159
	v_pk_mul_f32 v[124:125], v[124:125], v[170:171]
	v_pk_mul_f32 v[158:159], v[122:123], v[120:121]
	v_cvt_pk_bf16_f32 v120, v124, v125
	v_cvt_pk_bf16_f32 v121, v126, v127
	v_cvt_pk_bf16_f32 v122, v156, v157
	v_cvt_pk_bf16_f32 v123, v158, v159
	global_store_dwordx4 v[160:161], v[120:123], off
	v_pk_mul_f32 v[170:171], v[124:125], v[124:125]
	s_nop 1
	v_mov_b32_e32 v122, v172
	v_mov_b32_e32 v123, v173
	v_mov_b32_e32 v124, v174
	v_mov_b32_e32 v125, v175
	v_pk_mul_f32 v[120:121], v[158:159], v[158:159]
	v_pk_mul_f32 v[126:127], v[126:127], v[126:127]
	v_pk_mul_f32 v[156:157], v[156:157], v[156:157]
	v_lshlrev_b32_e32 v158, 16, v122
	v_and_b32_e32 v159, 0xffff0000, v122
	v_lshlrev_b32_e32 v122, 16, v123
	v_and_b32_e32 v123, 0xffff0000, v123
	v_pk_mul_f32 v[118:119], v[118:119], v[122:123]
	v_lshlrev_b32_e32 v122, 16, v124
	v_and_b32_e32 v123, 0xffff0000, v124
	v_pk_mul_f32 v[122:123], v[112:113], v[122:123]
	v_lshlrev_b32_e32 v112, 16, v125
	v_and_b32_e32 v113, 0xffff0000, v125
	v_pk_mul_f32 v[116:117], v[116:117], v[158:159]
	v_pk_mul_f32 v[124:125], v[114:115], v[112:113]
	v_cvt_pk_bf16_f32 v112, v116, v117
	v_cvt_pk_bf16_f32 v113, v118, v119
	v_cvt_pk_bf16_f32 v114, v122, v123
	v_cvt_pk_bf16_f32 v115, v124, v125
	global_store_dwordx4 v[160:161], v[112:115], off offset:256
	s_nop 1
	v_pk_mul_f32 v[112:113], v[116:117], v[116:117]
	v_pk_mul_f32 v[114:115], v[118:119], v[118:119]
	v_pk_mul_f32 v[116:117], v[122:123], v[122:123]
	v_add_f32_e32 v122, v170, v171
	v_add_f32_e32 v112, v112, v113
	v_add_f32_e32 v122, v126, v122
	v_add_f32_e32 v112, v114, v112
	v_add_f32_e32 v122, v127, v122
	v_add_f32_e32 v112, v115, v112
	v_add_f32_e32 v122, v156, v122
	v_add_f32_e32 v112, v116, v112
	v_pk_mul_f32 v[118:119], v[124:125], v[124:125]
	v_add_f32_e32 v122, v157, v122
	v_add_f32_e32 v112, v117, v112
	v_add_f32_e32 v120, v120, v122
	v_add_f32_e32 v112, v118, v112
	v_add_f32_e32 v120, v121, v120
	v_add_f32_e32 v112, v119, v112
	v_add_f32_e32 v112, v120, v112
	ds_bpermute_b32 v113, v154, v112
	s_waitcnt lgkmcnt(0)
	v_add_f32_e32 v112, v112, v113
	ds_bpermute_b32 v113, v153, v112
	s_and_saveexec_b64 s[40:41], vcc
	s_cbranch_execz .LBB0_1673
	v_lshl_add_u32 v114, v140, 4, s42
	v_readlane_b32 s4, v238, 28
	v_ashrrev_i32_e32 v115, 31, v114
	v_readlane_b32 s5, v238, 29
	s_waitcnt lgkmcnt(0)
	v_add_f32_e32 v112, v112, v113
	v_lshl_add_u64 v[114:115], v[114:115], 2, s[4:5]
	global_store_dword v[114:115], v112, off
; DI float blo(unsigned w) { return __uint_as_float(w << 16); }
; DI float bhi(unsigned w) { return __uint_as_float(w & 0xffff0000u); }
; DI u32x4 pk8(f32x4 a, f32x4 b) { u32x4 r; r.x = pk2(a[0], a[1]); r.y = pk2(a[2], a[3]); r.z = pk2(b[0], b[1]); r.w = pk2(b[2], b[3]); return r; }
;     DI void operator()(const Acc& acc, const pg8::Unit& u, int wr, int wc, int fr, int fq) const {
;     ...
;             for (int m = 0; m < 4; ++m) { const int row = row0 + ai * 128 + m * 16; float ss = 0.f;
; #pragma unroll
;                 for (int bj = 0; bj < 2; ++bj) { f32x4 v0 = acc[ai][bj][m][0], v1 = acc[ai][bj][m][1]; const size_t off = (size_t)row * 1024 + c0 + bj * 128;
;                     if (gate) { const u32x4 gw = *(const u32x4*)(gate + off);
;                         v0[0] *= blo(gw.x); v0[1] *= bhi(gw.x); v0[2] *= blo(gw.y); v0[3] *= bhi(gw.y); v1[0] *= blo(gw.z); v1[1] *= bhi(gw.z); v1[2] *= blo(gw.w); v1[3] *= bhi(gw.w); }
;                     *(u32x4*)(t + off) = pk8(v0, v1);
;                     ss += v0[0] * v0[0] + v0[1] * v0[1] + v0[2] * v0[2] + v0[3] * v0[3] + v1[0] * v1[0] + v1[1] * v1[1] + v1[2] * v1[2] + v1[3] * v1[3]; }
;                 ss += __shfl_xor(ss, 16); ss += __shfl_xor(ss, 32);
;                 if (fq == 0) ssq[row * 16 + u.pn * 4 + wc] = ss;
.LBB0_1673:
	s_or_b64 exec, exec, s[40:41]
	v_add_u32_e32 v112, 16, v140
	s_waitcnt lgkmcnt(0)
	v_ashrrev_i32_e32 v113, 31, v112
	v_lshlrev_b64 v[114:115], 10, v[112:113]
	v_lshl_add_u64 v[114:115], v[114:115], 0, v[138:139]
	v_readlane_b32 s4, v237, 44
	v_lshlrev_b64 v[118:119], 1, v[114:115]
	v_readlane_b32 s5, v237, 45
	s_nop 1
	v_lshl_add_u64 v[120:121], s[4:5], 0, v[118:119]
	s_nop 1
	v_mov_b32_e32 v114, v176
	v_mov_b32_e32 v115, v177
	v_mov_b32_e32 v116, v178
	v_mov_b32_e32 v117, v179
	v_lshl_add_u64 v[118:119], s[2:3], 0, v[118:119]
	v_lshlrev_b32_e32 v122, 16, v114
	v_and_b32_e32 v123, 0xffff0000, v114
	v_lshlrev_b32_e32 v114, 16, v115
	v_and_b32_e32 v115, 0xffff0000, v115
	v_pk_mul_f32 v[110:111], v[110:111], v[114:115]
	v_lshlrev_b32_e32 v114, 16, v116
	v_and_b32_e32 v115, 0xffff0000, v116
	v_pk_mul_f32 v[114:115], v[104:105], v[114:115]
	v_lshlrev_b32_e32 v104, 16, v117
	v_and_b32_e32 v105, 0xffff0000, v117
	v_pk_mul_f32 v[108:109], v[108:109], v[122:123]
	v_pk_mul_f32 v[116:117], v[106:107], v[104:105]
	v_cvt_pk_bf16_f32 v104, v108, v109
	v_cvt_pk_bf16_f32 v105, v110, v111
	v_cvt_pk_bf16_f32 v106, v114, v115
	v_cvt_pk_bf16_f32 v107, v116, v117
	global_store_dwordx4 v[118:119], v[104:107], off
	s_nop 1
	v_mov_b32_e32 v104, v188
	v_mov_b32_e32 v105, v189
	v_mov_b32_e32 v106, v190
	v_mov_b32_e32 v107, v191
	v_pk_mul_f32 v[108:109], v[108:109], v[108:109]
	v_pk_mul_f32 v[110:111], v[110:111], v[110:111]
	v_pk_mul_f32 v[114:115], v[114:115], v[114:115]
	v_pk_mul_f32 v[116:117], v[116:117], v[116:117]
	v_lshlrev_b32_e32 v120, 16, v104
	v_and_b32_e32 v121, 0xffff0000, v104
	v_lshlrev_b32_e32 v104, 16, v105
	v_and_b32_e32 v105, 0xffff0000, v105
	v_pk_mul_f32 v[102:103], v[102:103], v[104:105]
	v_lshlrev_b32_e32 v104, 16, v106
	v_and_b32_e32 v105, 0xffff0000, v106
	v_pk_mul_f32 v[104:105], v[96:97], v[104:105]
	v_lshlrev_b32_e32 v96, 16, v107
	v_and_b32_e32 v97, 0xffff0000, v107
	v_pk_mul_f32 v[100:101], v[100:101], v[120:121]
	v_pk_mul_f32 v[106:107], v[98:99], v[96:97]
	v_cvt_pk_bf16_f32 v96, v100, v101
	v_cvt_pk_bf16_f32 v97, v102, v103
	v_cvt_pk_bf16_f32 v98, v104, v105
	v_cvt_pk_bf16_f32 v99, v106, v107
	global_store_dwordx4 v[118:119], v[96:99], off offset:256
	s_nop 1
	v_pk_mul_f32 v[96:97], v[100:101], v[100:101]
	v_pk_mul_f32 v[98:99], v[102:103], v[102:103]
	v_pk_mul_f32 v[100:101], v[104:105], v[104:105]
	v_add_f32_e32 v104, v108, v109
	v_add_f32_e32 v96, v96, v97
	v_add_f32_e32 v104, v110, v104
	v_add_f32_e32 v96, v98, v96
	v_add_f32_e32 v104, v111, v104
	v_add_f32_e32 v96, v99, v96
	v_add_f32_e32 v104, v114, v104
	v_add_f32_e32 v96, v100, v96
	v_pk_mul_f32 v[102:103], v[106:107], v[106:107]
	v_add_f32_e32 v104, v115, v104
	v_add_f32_e32 v96, v101, v96
	v_add_f32_e32 v104, v116, v104
	v_add_f32_e32 v96, v102, v96
	v_add_f32_e32 v104, v117, v104
	v_add_f32_e32 v96, v103, v96
	v_add_f32_e32 v96, v104, v96
	ds_bpermute_b32 v97, v154, v96
	s_waitcnt lgkmcnt(0)
	v_add_f32_e32 v96, v96, v97
	ds_bpermute_b32 v97, v153, v96
	s_and_saveexec_b64 s[40:41], vcc
	s_cbranch_execz .LBB0_1675
	v_lshl_add_u32 v98, v112, 4, s42
	v_readlane_b32 s4, v238, 28
	v_ashrrev_i32_e32 v99, 31, v98
	v_readlane_b32 s5, v238, 29
	s_waitcnt lgkmcnt(0)
	v_add_f32_e32 v96, v96, v97
	v_lshl_add_u64 v[98:99], v[98:99], 2, s[4:5]
	global_store_dword v[98:99], v96, off
.LBB0_1675:
	s_or_b64 exec, exec, s[40:41]
	v_add_u32_e32 v96, 32, v140
	s_waitcnt lgkmcnt(0)
	v_ashrrev_i32_e32 v97, 31, v96
	v_lshlrev_b64 v[98:99], 10, v[96:97]
	v_lshl_add_u64 v[98:99], v[98:99], 0, v[138:139]
	v_readlane_b32 s4, v237, 44
	v_lshlrev_b64 v[102:103], 1, v[98:99]
	v_readlane_b32 s5, v237, 45
	s_nop 1
	v_lshl_add_u64 v[104:105], s[4:5], 0, v[102:103]
	s_nop 1
	v_mov_b32_e32 v98, v192
	v_mov_b32_e32 v99, v193
	v_mov_b32_e32 v100, v194
	v_mov_b32_e32 v101, v195
	v_lshl_add_u64 v[102:103], s[2:3], 0, v[102:103]
	v_lshlrev_b32_e32 v106, 16, v98
	v_and_b32_e32 v107, 0xffff0000, v98
	v_lshlrev_b32_e32 v98, 16, v99
	v_and_b32_e32 v99, 0xffff0000, v99
	v_pk_mul_f32 v[94:95], v[94:95], v[98:99]
	v_lshlrev_b32_e32 v98, 16, v100
	v_and_b32_e32 v99, 0xffff0000, v100
	v_pk_mul_f32 v[98:99], v[88:89], v[98:99]
	v_lshlrev_b32_e32 v88, 16, v101
	v_and_b32_e32 v89, 0xffff0000, v101
	v_pk_mul_f32 v[92:93], v[92:93], v[106:107]
	v_pk_mul_f32 v[100:101], v[90:91], v[88:89]
	v_cvt_pk_bf16_f32 v88, v92, v93
	v_cvt_pk_bf16_f32 v89, v94, v95
	v_cvt_pk_bf16_f32 v90, v98, v99
	v_cvt_pk_bf16_f32 v91, v100, v101
	global_store_dwordx4 v[102:103], v[88:91], off
	s_nop 1
	v_mov_b32_e32 v88, v196
	v_mov_b32_e32 v89, v197
	v_mov_b32_e32 v90, v198
	v_mov_b32_e32 v91, v199
	v_pk_mul_f32 v[92:93], v[92:93], v[92:93]
	v_pk_mul_f32 v[94:95], v[94:95], v[94:95]
	v_pk_mul_f32 v[98:99], v[98:99], v[98:99]
	v_pk_mul_f32 v[100:101], v[100:101], v[100:101]
	v_lshlrev_b32_e32 v104, 16, v88
	v_and_b32_e32 v105, 0xffff0000, v88
	v_lshlrev_b32_e32 v88, 16, v89
	v_and_b32_e32 v89, 0xffff0000, v89
	v_pk_mul_f32 v[86:87], v[86:87], v[88:89]
	v_lshlrev_b32_e32 v88, 16, v90
	v_and_b32_e32 v89, 0xffff0000, v90
	v_pk_mul_f32 v[88:89], v[80:81], v[88:89]
	v_lshlrev_b32_e32 v80, 16, v91
	v_and_b32_e32 v81, 0xffff0000, v91
	v_pk_mul_f32 v[84:85], v[84:85], v[104:105]
	v_pk_mul_f32 v[90:91], v[82:83], v[80:81]
	v_cvt_pk_bf16_f32 v80, v84, v85
	v_cvt_pk_bf16_f32 v81, v86, v87
	v_cvt_pk_bf16_f32 v82, v88, v89
	v_cvt_pk_bf16_f32 v83, v90, v91
	global_store_dwordx4 v[102:103], v[80:83], off offset:256
	s_nop 1
	v_pk_mul_f32 v[80:81], v[84:85], v[84:85]
	v_pk_mul_f32 v[82:83], v[86:87], v[86:87]
	v_pk_mul_f32 v[84:85], v[88:89], v[88:89]
	v_add_f32_e32 v88, v92, v93
	v_add_f32_e32 v80, v80, v81
	v_add_f32_e32 v88, v94, v88
	v_add_f32_e32 v80, v82, v80
	v_add_f32_e32 v88, v95, v88
	v_add_f32_e32 v80, v83, v80
	v_add_f32_e32 v88, v98, v88
	v_add_f32_e32 v80, v84, v80
	v_pk_mul_f32 v[86:87], v[90:91], v[90:91]
	v_add_f32_e32 v88, v99, v88
	v_add_f32_e32 v80, v85, v80
	v_add_f32_e32 v88, v100, v88
	v_add_f32_e32 v80, v86, v80
	v_add_f32_e32 v88, v101, v88
	v_add_f32_e32 v80, v87, v80
	v_add_f32_e32 v80, v88, v80
	ds_bpermute_b32 v81, v154, v80
	s_waitcnt lgkmcnt(0)
	v_add_f32_e32 v80, v80, v81
	ds_bpermute_b32 v81, v153, v80
	s_and_saveexec_b64 s[40:41], vcc
	s_cbranch_execz .LBB0_1677
	v_lshl_add_u32 v82, v96, 4, s42
	v_readlane_b32 s4, v238, 28
	v_ashrrev_i32_e32 v83, 31, v82
	v_readlane_b32 s5, v238, 29
	s_waitcnt lgkmcnt(0)
	v_add_f32_e32 v80, v80, v81
	v_lshl_add_u64 v[82:83], v[82:83], 2, s[4:5]
	global_store_dword v[82:83], v80, off
; DI float blo(unsigned w) { return __uint_as_float(w << 16); }
; DI float bhi(unsigned w) { return __uint_as_float(w & 0xffff0000u); }
; DI u32x4 pk8(f32x4 a, f32x4 b) { u32x4 r; r.x = pk2(a[0], a[1]); r.y = pk2(a[2], a[3]); r.z = pk2(b[0], b[1]); r.w = pk2(b[2], b[3]); return r; }
;     DI void operator()(const Acc& acc, const pg8::Unit& u, int wr, int wc, int fr, int fq) const {
;     ...
;             for (int m = 0; m < 4; ++m) { const int row = row0 + ai * 128 + m * 16; float ss = 0.f;
; #pragma unroll
;                 for (int bj = 0; bj < 2; ++bj) { f32x4 v0 = acc[ai][bj][m][0], v1 = acc[ai][bj][m][1]; const size_t off = (size_t)row * 1024 + c0 + bj * 128;
;                     if (gate) { const u32x4 gw = *(const u32x4*)(gate + off);
;                         v0[0] *= blo(gw.x); v0[1] *= bhi(gw.x); v0[2] *= blo(gw.y); v0[3] *= bhi(gw.y); v1[0] *= blo(gw.z); v1[1] *= bhi(gw.z); v1[2] *= blo(gw.w); v1[3] *= bhi(gw.w); }
;                     *(u32x4*)(t + off) = pk8(v0, v1);
;                     ss += v0[0] * v0[0] + v0[1] * v0[1] + v0[2] * v0[2] + v0[3] * v0[3] + v1[0] * v1[0] + v1[1] * v1[1] + v1[2] * v1[2] + v1[3] * v1[3]; }
;                 ss += __shfl_xor(ss, 16); ss += __shfl_xor(ss, 32);
;                 if (fq == 0) ssq[row * 16 + u.pn * 4 + wc] = ss;
.LBB0_1677:
	s_or_b64 exec, exec, s[40:41]
	v_add_u32_e32 v80, 48, v140
	s_waitcnt lgkmcnt(0)
	v_ashrrev_i32_e32 v81, 31, v80
	v_lshlrev_b64 v[82:83], 10, v[80:81]
	v_lshl_add_u64 v[82:83], v[82:83], 0, v[138:139]
	v_readlane_b32 s4, v237, 44
	v_lshlrev_b64 v[86:87], 1, v[82:83]
	v_readlane_b32 s5, v237, 45
	s_nop 1
	v_lshl_add_u64 v[88:89], s[4:5], 0, v[86:87]
	s_nop 1
	v_mov_b32_e32 v82, v200
	v_mov_b32_e32 v83, v201
	v_mov_b32_e32 v84, v202
	v_mov_b32_e32 v85, v203
	v_lshl_add_u64 v[86:87], s[2:3], 0, v[86:87]
	v_lshlrev_b32_e32 v90, 16, v82
	v_and_b32_e32 v91, 0xffff0000, v82
	v_lshlrev_b32_e32 v82, 16, v83
	v_and_b32_e32 v83, 0xffff0000, v83
	v_pk_mul_f32 v[78:79], v[78:79], v[82:83]
	v_lshlrev_b32_e32 v82, 16, v84
	v_and_b32_e32 v83, 0xffff0000, v84
	v_pk_mul_f32 v[82:83], v[72:73], v[82:83]
	v_lshlrev_b32_e32 v72, 16, v85
	v_and_b32_e32 v73, 0xffff0000, v85
	v_pk_mul_f32 v[76:77], v[76:77], v[90:91]
	v_pk_mul_f32 v[84:85], v[74:75], v[72:73]
	v_cvt_pk_bf16_f32 v72, v76, v77
	v_cvt_pk_bf16_f32 v73, v78, v79
	v_cvt_pk_bf16_f32 v74, v82, v83
	v_cvt_pk_bf16_f32 v75, v84, v85
	global_store_dwordx4 v[86:87], v[72:75], off
	s_nop 1
	v_mov_b32_e32 v72, v204
	v_mov_b32_e32 v73, v205
	v_mov_b32_e32 v74, v206
	v_mov_b32_e32 v75, v207
	v_pk_mul_f32 v[76:77], v[76:77], v[76:77]
	v_pk_mul_f32 v[78:79], v[78:79], v[78:79]
	v_pk_mul_f32 v[82:83], v[82:83], v[82:83]
	v_pk_mul_f32 v[84:85], v[84:85], v[84:85]
	v_lshlrev_b32_e32 v88, 16, v72
	v_and_b32_e32 v89, 0xffff0000, v72
	v_lshlrev_b32_e32 v72, 16, v73
	v_and_b32_e32 v73, 0xffff0000, v73
	v_pk_mul_f32 v[70:71], v[70:71], v[72:73]
	v_lshlrev_b32_e32 v72, 16, v74
	v_and_b32_e32 v73, 0xffff0000, v74
	v_pk_mul_f32 v[72:73], v[64:65], v[72:73]
	v_lshlrev_b32_e32 v64, 16, v75
	v_and_b32_e32 v65, 0xffff0000, v75
	v_pk_mul_f32 v[68:69], v[68:69], v[88:89]
	v_pk_mul_f32 v[74:75], v[66:67], v[64:65]
	v_cvt_pk_bf16_f32 v64, v68, v69
	v_cvt_pk_bf16_f32 v65, v70, v71
	v_cvt_pk_bf16_f32 v66, v72, v73
	v_cvt_pk_bf16_f32 v67, v74, v75
	global_store_dwordx4 v[86:87], v[64:67], off offset:256
	s_nop 1
	v_pk_mul_f32 v[64:65], v[68:69], v[68:69]
	v_pk_mul_f32 v[66:67], v[70:71], v[70:71]
	v_pk_mul_f32 v[68:69], v[72:73], v[72:73]
	v_add_f32_e32 v72, v76, v77
	v_add_f32_e32 v64, v64, v65
	v_add_f32_e32 v72, v78, v72
	v_add_f32_e32 v64, v66, v64
	v_add_f32_e32 v72, v79, v72
	v_add_f32_e32 v64, v67, v64
	v_add_f32_e32 v72, v82, v72
	v_add_f32_e32 v64, v68, v64
	v_pk_mul_f32 v[70:71], v[74:75], v[74:75]
	v_add_f32_e32 v72, v83, v72
	v_add_f32_e32 v64, v69, v64
	v_add_f32_e32 v72, v84, v72
	v_add_f32_e32 v64, v70, v64
	v_add_f32_e32 v72, v85, v72
	v_add_f32_e32 v64, v71, v64
	v_add_f32_e32 v64, v72, v64
	ds_bpermute_b32 v65, v154, v64
	s_waitcnt lgkmcnt(0)
	v_add_f32_e32 v64, v64, v65
	ds_bpermute_b32 v65, v153, v64
	s_and_saveexec_b64 s[40:41], vcc
	s_cbranch_execz .LBB0_1679
	v_lshl_add_u32 v66, v80, 4, s42
	v_readlane_b32 s4, v238, 28
	v_ashrrev_i32_e32 v67, 31, v66
	v_readlane_b32 s5, v238, 29
	s_waitcnt lgkmcnt(0)
	v_add_f32_e32 v64, v64, v65
	v_lshl_add_u64 v[66:67], v[66:67], 2, s[4:5]
	global_store_dword v[66:67], v64, off
.LBB0_1679:
	s_or_b64 exec, exec, s[40:41]
	v_add_u32_e32 v64, 0x80, v140
	s_waitcnt lgkmcnt(0)
	v_ashrrev_i32_e32 v65, 31, v64
	v_lshlrev_b64 v[66:67], 10, v[64:65]
	v_lshl_add_u64 v[66:67], v[66:67], 0, v[138:139]
	v_readlane_b32 s4, v237, 44
	v_lshlrev_b64 v[70:71], 1, v[66:67]
	v_readlane_b32 s5, v237, 45
	s_nop 1
	v_lshl_add_u64 v[72:73], s[4:5], 0, v[70:71]
	s_nop 1
	v_mov_b32_e32 v66, v208
	v_mov_b32_e32 v67, v209
	v_mov_b32_e32 v68, v210
	v_mov_b32_e32 v69, v211
	v_lshl_add_u64 v[70:71], s[2:3], 0, v[70:71]
	v_lshlrev_b32_e32 v74, 16, v66
	v_and_b32_e32 v75, 0xffff0000, v66
	v_lshlrev_b32_e32 v66, 16, v67
	v_and_b32_e32 v67, 0xffff0000, v67
	v_pk_mul_f32 v[62:63], v[62:63], v[66:67]
	v_lshlrev_b32_e32 v66, 16, v68
	v_and_b32_e32 v67, 0xffff0000, v68
	v_pk_mul_f32 v[66:67], v[56:57], v[66:67]
	v_lshlrev_b32_e32 v56, 16, v69
	v_and_b32_e32 v57, 0xffff0000, v69
	v_pk_mul_f32 v[60:61], v[60:61], v[74:75]
	v_pk_mul_f32 v[68:69], v[58:59], v[56:57]
	v_cvt_pk_bf16_f32 v56, v60, v61
	v_cvt_pk_bf16_f32 v57, v62, v63
	v_cvt_pk_bf16_f32 v58, v66, v67
	v_cvt_pk_bf16_f32 v59, v68, v69
	global_store_dwordx4 v[70:71], v[56:59], off
	s_nop 1
	v_mov_b32_e32 v56, v212
	v_mov_b32_e32 v57, v213
	v_mov_b32_e32 v58, v214
	v_mov_b32_e32 v59, v215
	v_pk_mul_f32 v[60:61], v[60:61], v[60:61]
	v_pk_mul_f32 v[62:63], v[62:63], v[62:63]
	v_pk_mul_f32 v[66:67], v[66:67], v[66:67]
	v_pk_mul_f32 v[68:69], v[68:69], v[68:69]
	v_lshlrev_b32_e32 v72, 16, v56
	v_and_b32_e32 v73, 0xffff0000, v56
	v_lshlrev_b32_e32 v56, 16, v57
	v_and_b32_e32 v57, 0xffff0000, v57
	v_pk_mul_f32 v[54:55], v[54:55], v[56:57]
	v_lshlrev_b32_e32 v56, 16, v58
	v_and_b32_e32 v57, 0xffff0000, v58
	v_pk_mul_f32 v[56:57], v[48:49], v[56:57]
	v_lshlrev_b32_e32 v48, 16, v59
	v_and_b32_e32 v49, 0xffff0000, v59
	v_pk_mul_f32 v[52:53], v[52:53], v[72:73]
	v_pk_mul_f32 v[58:59], v[50:51], v[48:49]
	v_cvt_pk_bf16_f32 v48, v52, v53
	v_cvt_pk_bf16_f32 v49, v54, v55
	v_cvt_pk_bf16_f32 v50, v56, v57
	v_cvt_pk_bf16_f32 v51, v58, v59
	global_store_dwordx4 v[70:71], v[48:51], off offset:256
	s_nop 1
	v_pk_mul_f32 v[48:49], v[52:53], v[52:53]
	v_pk_mul_f32 v[50:51], v[54:55], v[54:55]
	v_pk_mul_f32 v[52:53], v[56:57], v[56:57]
	v_add_f32_e32 v56, v60, v61
	v_add_f32_e32 v48, v48, v49
	v_add_f32_e32 v56, v62, v56
	v_add_f32_e32 v48, v50, v48
	v_add_f32_e32 v56, v63, v56
	v_add_f32_e32 v48, v51, v48
	v_add_f32_e32 v56, v66, v56
	v_add_f32_e32 v48, v52, v48
	v_pk_mul_f32 v[54:55], v[58:59], v[58:59]
	v_add_f32_e32 v56, v67, v56
	v_add_f32_e32 v48, v53, v48
	v_add_f32_e32 v56, v68, v56
	v_add_f32_e32 v48, v54, v48
	v_add_f32_e32 v56, v69, v56
	v_add_f32_e32 v48, v55, v48
	v_add_f32_e32 v48, v56, v48
	ds_bpermute_b32 v49, v154, v48
	s_waitcnt lgkmcnt(0)
	v_add_f32_e32 v48, v48, v49
	ds_bpermute_b32 v49, v153, v48
	s_and_saveexec_b64 s[40:41], vcc
	s_cbranch_execz .LBB0_1681
	v_lshl_add_u32 v50, v64, 4, s42
	v_readlane_b32 s4, v238, 28
	v_ashrrev_i32_e32 v51, 31, v50
	v_readlane_b32 s5, v238, 29
	s_waitcnt lgkmcnt(0)
	v_add_f32_e32 v48, v48, v49
	v_lshl_add_u64 v[50:51], v[50:51], 2, s[4:5]
	global_store_dword v[50:51], v48, off
; DI float blo(unsigned w) { return __uint_as_float(w << 16); }
; DI float bhi(unsigned w) { return __uint_as_float(w & 0xffff0000u); }
; DI u32x4 pk8(f32x4 a, f32x4 b) { u32x4 r; r.x = pk2(a[0], a[1]); r.y = pk2(a[2], a[3]); r.z = pk2(b[0], b[1]); r.w = pk2(b[2], b[3]); return r; }
;     DI void operator()(const Acc& acc, const pg8::Unit& u, int wr, int wc, int fr, int fq) const {
;     ...
;             for (int m = 0; m < 4; ++m) { const int row = row0 + ai * 128 + m * 16; float ss = 0.f;
; #pragma unroll
;                 for (int bj = 0; bj < 2; ++bj) { f32x4 v0 = acc[ai][bj][m][0], v1 = acc[ai][bj][m][1]; const size_t off = (size_t)row * 1024 + c0 + bj * 128;
;                     if (gate) { const u32x4 gw = *(const u32x4*)(gate + off);
;                         v0[0] *= blo(gw.x); v0[1] *= bhi(gw.x); v0[2] *= blo(gw.y); v0[3] *= bhi(gw.y); v1[0] *= blo(gw.z); v1[1] *= bhi(gw.z); v1[2] *= blo(gw.w); v1[3] *= bhi(gw.w); }
;                     *(u32x4*)(t + off) = pk8(v0, v1);
;                     ss += v0[0] * v0[0] + v0[1] * v0[1] + v0[2] * v0[2] + v0[3] * v0[3] + v1[0] * v1[0] + v1[1] * v1[1] + v1[2] * v1[2] + v1[3] * v1[3]; }
;                 ss += __shfl_xor(ss, 16); ss += __shfl_xor(ss, 32);
;                 if (fq == 0) ssq[row * 16 + u.pn * 4 + wc] = ss;
.LBB0_1681:
	s_or_b64 exec, exec, s[40:41]
	v_add_u32_e32 v48, 0x90, v140
	s_waitcnt lgkmcnt(0)
	v_ashrrev_i32_e32 v49, 31, v48
	v_lshlrev_b64 v[50:51], 10, v[48:49]
	v_lshl_add_u64 v[50:51], v[50:51], 0, v[138:139]
	v_readlane_b32 s4, v237, 44
	v_lshlrev_b64 v[54:55], 1, v[50:51]
	v_readlane_b32 s5, v237, 45
	s_nop 1
	v_lshl_add_u64 v[56:57], s[4:5], 0, v[54:55]
	s_nop 1
	v_mov_b32_e32 v50, v216
	v_mov_b32_e32 v51, v217
	v_mov_b32_e32 v52, v218
	v_mov_b32_e32 v53, v219
	v_lshl_add_u64 v[54:55], s[2:3], 0, v[54:55]
	v_lshlrev_b32_e32 v58, 16, v50
	v_and_b32_e32 v59, 0xffff0000, v50
	v_lshlrev_b32_e32 v50, 16, v51
	v_and_b32_e32 v51, 0xffff0000, v51
	v_pk_mul_f32 v[46:47], v[46:47], v[50:51]
	v_lshlrev_b32_e32 v50, 16, v52
	v_and_b32_e32 v51, 0xffff0000, v52
	v_pk_mul_f32 v[50:51], v[40:41], v[50:51]
	v_lshlrev_b32_e32 v40, 16, v53
	v_and_b32_e32 v41, 0xffff0000, v53
	v_pk_mul_f32 v[44:45], v[44:45], v[58:59]
	v_pk_mul_f32 v[52:53], v[42:43], v[40:41]
	v_cvt_pk_bf16_f32 v40, v44, v45
	v_cvt_pk_bf16_f32 v41, v46, v47
	v_cvt_pk_bf16_f32 v42, v50, v51
	v_cvt_pk_bf16_f32 v43, v52, v53
	global_store_dwordx4 v[54:55], v[40:43], off
	s_nop 1
	v_mov_b32_e32 v40, v220
	v_mov_b32_e32 v41, v221
	v_mov_b32_e32 v42, v222
	v_mov_b32_e32 v43, v223
	v_pk_mul_f32 v[44:45], v[44:45], v[44:45]
	v_pk_mul_f32 v[46:47], v[46:47], v[46:47]
	v_pk_mul_f32 v[50:51], v[50:51], v[50:51]
	v_pk_mul_f32 v[52:53], v[52:53], v[52:53]
	v_lshlrev_b32_e32 v56, 16, v40
	v_and_b32_e32 v57, 0xffff0000, v40
	v_lshlrev_b32_e32 v40, 16, v41
	v_and_b32_e32 v41, 0xffff0000, v41
	v_pk_mul_f32 v[38:39], v[38:39], v[40:41]
	v_lshlrev_b32_e32 v40, 16, v42
	v_and_b32_e32 v41, 0xffff0000, v42
	v_pk_mul_f32 v[40:41], v[32:33], v[40:41]
	v_lshlrev_b32_e32 v32, 16, v43
	v_and_b32_e32 v33, 0xffff0000, v43
	v_pk_mul_f32 v[36:37], v[36:37], v[56:57]
	v_pk_mul_f32 v[42:43], v[34:35], v[32:33]
	v_cvt_pk_bf16_f32 v32, v36, v37
	v_cvt_pk_bf16_f32 v33, v38, v39
	v_cvt_pk_bf16_f32 v34, v40, v41
	v_cvt_pk_bf16_f32 v35, v42, v43
	global_store_dwordx4 v[54:55], v[32:35], off offset:256
	s_nop 1
	v_pk_mul_f32 v[32:33], v[36:37], v[36:37]
	v_pk_mul_f32 v[34:35], v[38:39], v[38:39]
	v_pk_mul_f32 v[36:37], v[40:41], v[40:41]
	v_add_f32_e32 v40, v44, v45
	v_add_f32_e32 v32, v32, v33
	v_add_f32_e32 v40, v46, v40
	v_add_f32_e32 v32, v34, v32
	v_add_f32_e32 v40, v47, v40
	v_add_f32_e32 v32, v35, v32
	v_add_f32_e32 v40, v50, v40
	v_add_f32_e32 v32, v36, v32
	v_pk_mul_f32 v[38:39], v[42:43], v[42:43]
	v_add_f32_e32 v40, v51, v40
	v_add_f32_e32 v32, v37, v32
	v_add_f32_e32 v40, v52, v40
	v_add_f32_e32 v32, v38, v32
	v_add_f32_e32 v40, v53, v40
	v_add_f32_e32 v32, v39, v32
	v_add_f32_e32 v32, v40, v32
	ds_bpermute_b32 v33, v154, v32
	s_waitcnt lgkmcnt(0)
	v_add_f32_e32 v32, v32, v33
	ds_bpermute_b32 v33, v153, v32
	s_and_saveexec_b64 s[40:41], vcc
	s_cbranch_execz .LBB0_1683
	v_lshl_add_u32 v34, v48, 4, s42
	v_readlane_b32 s4, v238, 28
	v_ashrrev_i32_e32 v35, 31, v34
	v_readlane_b32 s5, v238, 29
	s_waitcnt lgkmcnt(0)
	v_add_f32_e32 v32, v32, v33
	v_lshl_add_u64 v[34:35], v[34:35], 2, s[4:5]
	global_store_dword v[34:35], v32, off
; DI float blo(unsigned w) { return __uint_as_float(w << 16); }
; DI float bhi(unsigned w) { return __uint_as_float(w & 0xffff0000u); }
; DI u32x4 pk8(f32x4 a, f32x4 b) { u32x4 r; r.x = pk2(a[0], a[1]); r.y = pk2(a[2], a[3]); r.z = pk2(b[0], b[1]); r.w = pk2(b[2], b[3]); return r; }
;     DI void operator()(const Acc& acc, const pg8::Unit& u, int wr, int wc, int fr, int fq) const {
;     ...
;             for (int m = 0; m < 4; ++m) { const int row = row0 + ai * 128 + m * 16; float ss = 0.f;
; #pragma unroll
;                 for (int bj = 0; bj < 2; ++bj) { f32x4 v0 = acc[ai][bj][m][0], v1 = acc[ai][bj][m][1]; const size_t off = (size_t)row * 1024 + c0 + bj * 128;
;                     if (gate) { const u32x4 gw = *(const u32x4*)(gate + off);
;                         v0[0] *= blo(gw.x); v0[1] *= bhi(gw.x); v0[2] *= blo(gw.y); v0[3] *= bhi(gw.y); v1[0] *= blo(gw.z); v1[1] *= bhi(gw.z); v1[2] *= blo(gw.w); v1[3] *= bhi(gw.w); }
;                     *(u32x4*)(t + off) = pk8(v0, v1);
;                     ss += v0[0] * v0[0] + v0[1] * v0[1] + v0[2] * v0[2] + v0[3] * v0[3] + v1[0] * v1[0] + v1[1] * v1[1] + v1[2] * v1[2] + v1[3] * v1[3]; }
;                 ss += __shfl_xor(ss, 16); ss += __shfl_xor(ss, 32);
;                 if (fq == 0) ssq[row * 16 + u.pn * 4 + wc] = ss;
.LBB0_1683:
	s_or_b64 exec, exec, s[40:41]
	v_add_u32_e32 v32, 0xa0, v140
	s_waitcnt lgkmcnt(0)
	v_ashrrev_i32_e32 v33, 31, v32
	v_lshlrev_b64 v[34:35], 10, v[32:33]
	v_lshl_add_u64 v[34:35], v[34:35], 0, v[138:139]
	v_readlane_b32 s4, v237, 44
	v_lshlrev_b64 v[38:39], 1, v[34:35]
	v_readlane_b32 s5, v237, 45
	s_nop 1
	v_lshl_add_u64 v[40:41], s[4:5], 0, v[38:39]
	s_nop 1
	v_mov_b32_e32 v34, v224
	v_mov_b32_e32 v35, v225
	v_mov_b32_e32 v36, v226
	v_mov_b32_e32 v37, v227
	v_lshl_add_u64 v[38:39], s[2:3], 0, v[38:39]
	v_lshlrev_b32_e32 v42, 16, v34
	v_and_b32_e32 v43, 0xffff0000, v34
	v_lshlrev_b32_e32 v34, 16, v35
	v_and_b32_e32 v35, 0xffff0000, v35
	v_pk_mul_f32 v[30:31], v[30:31], v[34:35]
	v_lshlrev_b32_e32 v34, 16, v36
	v_and_b32_e32 v35, 0xffff0000, v36
	v_pk_mul_f32 v[34:35], v[24:25], v[34:35]
	v_lshlrev_b32_e32 v24, 16, v37
	v_and_b32_e32 v25, 0xffff0000, v37
	v_pk_mul_f32 v[28:29], v[28:29], v[42:43]
	v_pk_mul_f32 v[36:37], v[26:27], v[24:25]
	v_cvt_pk_bf16_f32 v24, v28, v29
	v_cvt_pk_bf16_f32 v25, v30, v31
	v_cvt_pk_bf16_f32 v26, v34, v35
	v_cvt_pk_bf16_f32 v27, v36, v37
	global_store_dwordx4 v[38:39], v[24:27], off
	s_nop 1
	v_mov_b32_e32 v24, v240
	v_mov_b32_e32 v25, v241
	v_mov_b32_e32 v26, v242
	v_mov_b32_e32 v27, v243
	v_pk_mul_f32 v[28:29], v[28:29], v[28:29]
	v_pk_mul_f32 v[30:31], v[30:31], v[30:31]
	v_pk_mul_f32 v[34:35], v[34:35], v[34:35]
	v_pk_mul_f32 v[36:37], v[36:37], v[36:37]
	v_lshlrev_b32_e32 v40, 16, v24
	v_and_b32_e32 v41, 0xffff0000, v24
	v_lshlrev_b32_e32 v24, 16, v25
	v_and_b32_e32 v25, 0xffff0000, v25
	v_pk_mul_f32 v[22:23], v[22:23], v[24:25]
	v_lshlrev_b32_e32 v24, 16, v26
	v_and_b32_e32 v25, 0xffff0000, v26
	v_pk_mul_f32 v[24:25], v[16:17], v[24:25]
	v_lshlrev_b32_e32 v16, 16, v27
	v_and_b32_e32 v17, 0xffff0000, v27
	v_pk_mul_f32 v[20:21], v[20:21], v[40:41]
	v_pk_mul_f32 v[26:27], v[18:19], v[16:17]
	v_cvt_pk_bf16_f32 v16, v20, v21
	v_cvt_pk_bf16_f32 v17, v22, v23
	v_cvt_pk_bf16_f32 v18, v24, v25
	v_cvt_pk_bf16_f32 v19, v26, v27
	global_store_dwordx4 v[38:39], v[16:19], off offset:256
	s_nop 1
	v_pk_mul_f32 v[16:17], v[20:21], v[20:21]
	v_pk_mul_f32 v[18:19], v[22:23], v[22:23]
	v_pk_mul_f32 v[20:21], v[24:25], v[24:25]
	v_add_f32_e32 v24, v28, v29
	v_add_f32_e32 v16, v16, v17
	v_add_f32_e32 v24, v30, v24
	v_add_f32_e32 v16, v18, v16
	v_add_f32_e32 v24, v31, v24
	v_add_f32_e32 v16, v19, v16
	v_add_f32_e32 v24, v34, v24
	v_add_f32_e32 v16, v20, v16
	v_pk_mul_f32 v[22:23], v[26:27], v[26:27]
	v_add_f32_e32 v24, v35, v24
	v_add_f32_e32 v16, v21, v16
	v_add_f32_e32 v24, v36, v24
	v_add_f32_e32 v16, v22, v16
	v_add_f32_e32 v24, v37, v24
	v_add_f32_e32 v16, v23, v16
	v_add_f32_e32 v16, v24, v16
	ds_bpermute_b32 v17, v154, v16
	s_waitcnt lgkmcnt(0)
	v_add_f32_e32 v16, v16, v17
	ds_bpermute_b32 v17, v153, v16
	s_and_saveexec_b64 s[40:41], vcc
	s_cbranch_execz .LBB0_1685
	v_lshl_add_u32 v18, v32, 4, s42
	v_readlane_b32 s4, v238, 28
	v_ashrrev_i32_e32 v19, 31, v18
	v_readlane_b32 s5, v238, 29
	s_waitcnt lgkmcnt(0)
	v_add_f32_e32 v16, v16, v17
	v_lshl_add_u64 v[18:19], v[18:19], 2, s[4:5]
	global_store_dword v[18:19], v16, off
.LBB0_1685:
	s_or_b64 exec, exec, s[40:41]
	v_add_u32_e32 v16, 0xb0, v140
	s_waitcnt lgkmcnt(0)
	v_ashrrev_i32_e32 v17, 31, v16
	v_lshlrev_b64 v[18:19], 10, v[16:17]
	v_lshl_add_u64 v[18:19], v[18:19], 0, v[138:139]
	v_readlane_b32 s4, v237, 44
	v_lshlrev_b64 v[22:23], 1, v[18:19]
	v_readlane_b32 s5, v237, 45
	s_nop 1
	v_lshl_add_u64 v[24:25], s[4:5], 0, v[22:23]
	s_nop 1
	v_mov_b32_e32 v18, v244
	v_mov_b32_e32 v19, v245
	v_mov_b32_e32 v20, v246
	v_mov_b32_e32 v21, v247
	v_lshl_add_u64 v[22:23], s[2:3], 0, v[22:23]
	v_lshlrev_b32_e32 v26, 16, v18
	v_and_b32_e32 v27, 0xffff0000, v18
	v_lshlrev_b32_e32 v18, 16, v19
	v_and_b32_e32 v19, 0xffff0000, v19
	v_pk_mul_f32 v[14:15], v[14:15], v[18:19]
	v_lshlrev_b32_e32 v18, 16, v20
	v_and_b32_e32 v19, 0xffff0000, v20
	v_pk_mul_f32 v[18:19], v[8:9], v[18:19]
	v_lshlrev_b32_e32 v8, 16, v21
	v_and_b32_e32 v9, 0xffff0000, v21
	v_pk_mul_f32 v[12:13], v[12:13], v[26:27]
	v_pk_mul_f32 v[20:21], v[10:11], v[8:9]
	v_cvt_pk_bf16_f32 v8, v12, v13
	v_cvt_pk_bf16_f32 v9, v14, v15
	v_cvt_pk_bf16_f32 v10, v18, v19
	v_cvt_pk_bf16_f32 v11, v20, v21
	global_store_dwordx4 v[22:23], v[8:11], off
	s_nop 1
	v_mov_b32_e32 v8, v248
	v_mov_b32_e32 v9, v249
	v_mov_b32_e32 v10, v250
	v_mov_b32_e32 v11, v251
	v_pk_mul_f32 v[12:13], v[12:13], v[12:13]
	v_pk_mul_f32 v[14:15], v[14:15], v[14:15]
	v_pk_mul_f32 v[18:19], v[18:19], v[18:19]
	v_pk_mul_f32 v[20:21], v[20:21], v[20:21]
	v_lshlrev_b32_e32 v24, 16, v8
	v_and_b32_e32 v25, 0xffff0000, v8
	v_lshlrev_b32_e32 v8, 16, v9
	v_and_b32_e32 v9, 0xffff0000, v9
	v_pk_mul_f32 v[6:7], v[6:7], v[8:9]
	v_lshlrev_b32_e32 v8, 16, v10
	v_and_b32_e32 v9, 0xffff0000, v10
	v_pk_mul_f32 v[8:9], v[0:1], v[8:9]
	v_lshlrev_b32_e32 v0, 16, v11
	v_and_b32_e32 v1, 0xffff0000, v11
	v_pk_mul_f32 v[4:5], v[4:5], v[24:25]
	v_pk_mul_f32 v[10:11], v[2:3], v[0:1]
	v_cvt_pk_bf16_f32 v0, v4, v5
	v_cvt_pk_bf16_f32 v1, v6, v7
	v_cvt_pk_bf16_f32 v2, v8, v9
	v_cvt_pk_bf16_f32 v3, v10, v11
	global_store_dwordx4 v[22:23], v[0:3], off offset:256
	s_nop 1
	v_pk_mul_f32 v[0:1], v[4:5], v[4:5]
	v_pk_mul_f32 v[2:3], v[6:7], v[6:7]
	v_pk_mul_f32 v[4:5], v[8:9], v[8:9]
	v_add_f32_e32 v8, v12, v13
	v_add_f32_e32 v0, v0, v1
	v_add_f32_e32 v8, v14, v8
	v_add_f32_e32 v0, v2, v0
	v_add_f32_e32 v8, v15, v8
	v_add_f32_e32 v0, v3, v0
	v_add_f32_e32 v8, v18, v8
	v_add_f32_e32 v0, v4, v0
	v_pk_mul_f32 v[6:7], v[10:11], v[10:11]
	v_add_f32_e32 v8, v19, v8
	v_add_f32_e32 v0, v5, v0
	v_add_f32_e32 v8, v20, v8
	v_add_f32_e32 v0, v6, v0
	v_add_f32_e32 v8, v21, v8
	v_add_f32_e32 v0, v7, v0
	v_add_f32_e32 v0, v8, v0
	ds_bpermute_b32 v1, v154, v0
	s_waitcnt lgkmcnt(0)
	v_add_f32_e32 v0, v0, v1
	ds_bpermute_b32 v1, v153, v0
	s_and_saveexec_b64 s[40:41], vcc
	s_cbranch_execz .LBB0_1661
	v_lshl_add_u32 v2, v16, 4, s42
	v_readlane_b32 s4, v238, 28
	v_ashrrev_i32_e32 v3, 31, v2
	v_readlane_b32 s5, v238, 29
	s_waitcnt lgkmcnt(0)
	v_add_f32_e32 v0, v0, v1
	v_lshl_add_u64 v[2:3], v[2:3], 2, s[4:5]
	global_store_dword v[2:3], v0, off
	s_branch .LBB0_1661

; __global__ void __launch_bounds__(512) fwd_kernel(Params P) {
	.amdhsa_kernel _Z10fwd_kernel6Params
		.amdhsa_group_segment_fixed_size 256
		.amdhsa_private_segment_fixed_size 0
		.amdhsa_kernarg_size 448
		.amdhsa_user_sgpr_count 2
		.amdhsa_user_sgpr_dispatch_ptr 0
		.amdhsa_user_sgpr_queue_ptr 0
		.amdhsa_user_sgpr_kernarg_segment_ptr 1
		.amdhsa_user_sgpr_dispatch_id 0
		.amdhsa_user_sgpr_kernarg_preload_length 0
		.amdhsa_user_sgpr_kernarg_preload_offset 0
		.amdhsa_user_sgpr_private_segment_size 0
		.amdhsa_uses_dynamic_stack 0
		.amdhsa_enable_private_segment 0
		.amdhsa_system_sgpr_workgroup_id_x 1
		.amdhsa_system_sgpr_workgroup_id_y 0
		.amdhsa_system_sgpr_workgroup_id_z 0
		.amdhsa_system_sgpr_workgroup_info 0
		.amdhsa_system_vgpr_workitem_id 2
		.amdhsa_next_free_vgpr 256
		.amdhsa_next_free_sgpr 102
		.amdhsa_accum_offset 256
		.amdhsa_reserve_vcc 1
		.amdhsa_float_round_mode_32 0
		.amdhsa_float_round_mode_16_64 0
		.amdhsa_float_denorm_mode_32 3
		.amdhsa_float_denorm_mode_16_64 3
		.amdhsa_dx10_clamp 1
		.amdhsa_ieee_mode 1
		.amdhsa_fp16_overflow 0
		.amdhsa_tg_split 0
		.amdhsa_exception_fp_ieee_invalid_op 0
		.amdhsa_exception_fp_denorm_src 0
		.amdhsa_exception_fp_ieee_div_zero 0
		.amdhsa_exception_fp_ieee_overflow 0
		.amdhsa_exception_fp_ieee_underflow 0
		.amdhsa_exception_fp_ieee_inexact 0
		.amdhsa_exception_int_div_zero 0
	.end_amdhsa_kernel

; __global__ void __launch_bounds__(512) fwd_kernel(Params P) {
amdhsa.kernels:
  - .agpr_count:     0
    .args:
      - .offset:         0
        .size:           192
        .value_kind:     by_value
      - .offset:         192
        .size:           4
        .value_kind:     hidden_block_count_x
      - .offset:         196
        .size:           4
        .value_kind:     hidden_block_count_y
      - .offset:         200
        .size:           4
        .value_kind:     hidden_block_count_z
      - .offset:         204
        .size:           2
        .value_kind:     hidden_group_size_x
      - .offset:         206
        .size:           2
        .value_kind:     hidden_group_size_y
      - .offset:         208
        .size:           2
        .value_kind:     hidden_group_size_z
      - .offset:         210
        .size:           2
        .value_kind:     hidden_remainder_x
      - .offset:         212
        .size:           2
        .value_kind:     hidden_remainder_y
      - .offset:         214
        .size:           2
        .value_kind:     hidden_remainder_z
      - .offset:         232
        .size:           8
        .value_kind:     hidden_global_offset_x
      - .offset:         240
        .size:           8
        .value_kind:     hidden_global_offset_y
      - .offset:         248
        .size:           8
        .value_kind:     hidden_global_offset_z
      - .offset:         256
        .size:           2
        .value_kind:     hidden_grid_dims
      - .offset:         280
        .size:           8
        .value_kind:     hidden_multigrid_sync_arg
      - .offset:         312
        .size:           4
        .value_kind:     hidden_dynamic_lds_size
    .group_segment_fixed_size: 256
    .kernarg_segment_align: 8
    .kernarg_segment_size: 448
    .language:       OpenCL C
    .language_version:
      - 2
      - 0
    .max_flat_workgroup_size: 512
    .name:           _Z10fwd_kernel6Params
    .private_segment_fixed_size: 0
    .sgpr_count:     108
    .sgpr_spill_count: 189
    .symbol:         _Z10fwd_kernel6Params.kd
    .uniform_work_group_size: 1
    .uses_dynamic_stack: false
    .vgpr_count:     256
    .vgpr_spill_count: 0
    .wavefront_size: 64
